# M-phase MFMAs merged into one 32-run ordered m,(block,n),k: each A-fragment pair held for 8 consecutive MFMAs, mid-phase setprio pair removed; on top of saddr loads + P13 gain hoist
# speedup vs baseline: 1.0044x; 1.0044x over previous
.LBB0_1790:
	ds_read_b128 v[146:149], v159
	ds_read_b128 v[150:153], v159 offset:1024
	ds_read_b128 v[164:167], v159 offset:2048
	ds_read_b128 v[168:171], v159 offset:3072
	ds_read_b128 v[172:175], v160
	ds_read_b128 v[176:179], v160 offset:1024
	ds_read_b128 v[186:189], v160 offset:2048
	ds_read_b128 v[190:193], v160 offset:3072
	s_add_u32 s79, s6, 0xfff00080
	s_addc_u32 s80, s7, -1
	s_cmp_eq_u32 s78, 60
	s_cselect_b32 s91, s45, s80
	s_cselect_b32 s90, s74, s79
	s_cselect_b32 s89, s43, s77
	s_cselect_b32 s88, s75, s76
	s_add_i32 m0, s33, 0xc000
	ds_read_b128 v[194:197], v161
	ds_read_b128 v[198:201], v161 offset:1024
	ds_read_b128 v[202:205], v161 offset:2048
	ds_read_b128 v[206:209], v161 offset:3072
	ds_read_b128 v[210:213], v161 offset:4096
	ds_read_b128 v[214:217], v161 offset:5120
	ds_read_b128 v[218:221], v161 offset:6144
	ds_read_b128 v[222:225], v161 offset:7168
	global_load_lds_dwordx4 v138, s[6:7]
	s_add_i32 m0, s33, 0xe000
	s_nop 0
	global_load_lds_dwordx4 v140, s[6:7]
	s_waitcnt vmcnt(8)
	s_waitcnt lgkmcnt(0)
	s_barrier
	s_setprio 1
	s_waitcnt lgkmcnt(0)
	v_mfma_f32_16x16x32_bf16 v[126:129], v[146:149], v[194:197], v[126:129]
	v_mfma_f32_16x16x32_bf16 v[126:129], v[150:153], v[198:201], v[126:129]
	v_mfma_f32_16x16x32_bf16 v[122:125], v[164:167], v[194:197], v[122:125]
	v_mfma_f32_16x16x32_bf16 v[122:125], v[168:171], v[198:201], v[122:125]
	v_mfma_f32_16x16x32_bf16 v[118:121], v[172:175], v[194:197], v[118:121]
	v_mfma_f32_16x16x32_bf16 v[118:121], v[176:179], v[198:201], v[118:121]
	v_mfma_f32_16x16x32_bf16 v[110:113], v[186:189], v[194:197], v[110:113]
	v_mfma_f32_16x16x32_bf16 v[110:113], v[190:193], v[198:201], v[110:113]
	v_mfma_f32_16x16x32_bf16 v[114:117], v[146:149], v[202:205], v[114:117]
	v_mfma_f32_16x16x32_bf16 v[114:117], v[150:153], v[206:209], v[114:117]
	v_mfma_f32_16x16x32_bf16 v[106:109], v[164:167], v[202:205], v[106:109]
	v_mfma_f32_16x16x32_bf16 v[106:109], v[168:171], v[206:209], v[106:109]
	v_mfma_f32_16x16x32_bf16 v[102:105], v[172:175], v[202:205], v[102:105]
	v_mfma_f32_16x16x32_bf16 v[102:105], v[176:179], v[206:209], v[102:105]
	v_mfma_f32_16x16x32_bf16 v[94:97], v[186:189], v[202:205], v[94:97]
	v_mfma_f32_16x16x32_bf16 v[94:97], v[190:193], v[206:209], v[94:97]
	v_mfma_f32_16x16x32_bf16 v[98:101], v[146:149], v[210:213], v[98:101]
	v_mfma_f32_16x16x32_bf16 v[98:101], v[150:153], v[214:217], v[98:101]
	v_mfma_f32_16x16x32_bf16 v[90:93], v[164:167], v[210:213], v[90:93]
	v_mfma_f32_16x16x32_bf16 v[90:93], v[168:171], v[214:217], v[90:93]
	v_mfma_f32_16x16x32_bf16 v[86:89], v[172:175], v[210:213], v[86:89]
	v_mfma_f32_16x16x32_bf16 v[86:89], v[176:179], v[214:217], v[86:89]
	v_mfma_f32_16x16x32_bf16 v[78:81], v[186:189], v[210:213], v[78:81]
	v_mfma_f32_16x16x32_bf16 v[78:81], v[190:193], v[214:217], v[78:81]
	v_mfma_f32_16x16x32_bf16 v[82:85], v[146:149], v[218:221], v[82:85]
	v_mfma_f32_16x16x32_bf16 v[82:85], v[150:153], v[222:225], v[82:85]
	v_mfma_f32_16x16x32_bf16 v[74:77], v[164:167], v[218:221], v[74:77]
	v_mfma_f32_16x16x32_bf16 v[74:77], v[168:171], v[222:225], v[74:77]
	v_mfma_f32_16x16x32_bf16 v[70:73], v[172:175], v[218:221], v[70:73]
	v_mfma_f32_16x16x32_bf16 v[70:73], v[176:179], v[222:225], v[70:73]
	v_mfma_f32_16x16x32_bf16 v[66:69], v[186:189], v[218:221], v[66:69]
	v_mfma_f32_16x16x32_bf16 v[66:69], v[190:193], v[222:225], v[66:69]
	s_setprio 0
	s_barrier
	s_add_i32 s79, s69, s25
	s_add_u32 s98, s88, 0x80
	s_addc_u32 s99, s89, 0
	s_mov_b32 m0, s79
	ds_read_b128 v[194:197], v161 offset:16384
	ds_read_b128 v[198:201], v161 offset:17408
	ds_read_b128 v[202:205], v161 offset:18432
	ds_read_b128 v[206:209], v161 offset:19456
	ds_read_b128 v[210:213], v161 offset:20480
	ds_read_b128 v[214:217], v161 offset:21504
	ds_read_b128 v[218:221], v161 offset:22528
	ds_read_b128 v[222:225], v161 offset:23552
	global_load_lds_dwordx4 v132, s[88:89]
	s_add_i32 m0, s79, 0x2000
	s_add_u32 s80, s88, 0x100000
	s_addc_u32 s81, s89, 0
	s_add_i32 s79, s70, s25
	global_load_lds_dwordx4 v136, s[88:89]
	s_mov_b32 m0, s79
	global_load_lds_dwordx4 v132, s[80:81]
	s_add_i32 m0, s79, 0x2000
	s_nop 0
	global_load_lds_dwordx4 v136, s[80:81]
	s_add_u32 s100, s90, 0x80
	s_addc_u32 s101, s91, 0
	s_mov_b32 m0, s33
	s_nop 0
	global_load_lds_dwordx4 v130, s[90:91]
	s_mov_b32 m0, s35
	s_nop 0
	global_load_lds_dwordx4 v134, s[90:91]
	s_waitcnt vmcnt(8)
	s_waitcnt lgkmcnt(0)
	s_barrier
	s_setprio 1
	s_waitcnt lgkmcnt(0)
	v_mfma_f32_16x16x32_bf16 v[62:65], v[146:149], v[194:197], v[62:65]
	v_mfma_f32_16x16x32_bf16 v[62:65], v[150:153], v[198:201], v[62:65]
	v_mfma_f32_16x16x32_bf16 v[58:61], v[164:167], v[194:197], v[58:61]
	v_mfma_f32_16x16x32_bf16 v[58:61], v[168:171], v[198:201], v[58:61]
	v_mfma_f32_16x16x32_bf16 v[54:57], v[172:175], v[194:197], v[54:57]
	v_mfma_f32_16x16x32_bf16 v[54:57], v[176:179], v[198:201], v[54:57]
	v_mfma_f32_16x16x32_bf16 v[46:49], v[186:189], v[194:197], v[46:49]
	v_mfma_f32_16x16x32_bf16 v[46:49], v[190:193], v[198:201], v[46:49]
	v_mfma_f32_16x16x32_bf16 v[50:53], v[146:149], v[202:205], v[50:53]
	v_mfma_f32_16x16x32_bf16 v[50:53], v[150:153], v[206:209], v[50:53]
	v_mfma_f32_16x16x32_bf16 v[42:45], v[164:167], v[202:205], v[42:45]
	v_mfma_f32_16x16x32_bf16 v[42:45], v[168:171], v[206:209], v[42:45]
	v_mfma_f32_16x16x32_bf16 v[38:41], v[172:175], v[202:205], v[38:41]
	v_mfma_f32_16x16x32_bf16 v[38:41], v[176:179], v[206:209], v[38:41]
	v_mfma_f32_16x16x32_bf16 v[30:33], v[186:189], v[202:205], v[30:33]
	v_mfma_f32_16x16x32_bf16 v[30:33], v[190:193], v[206:209], v[30:33]
	v_mfma_f32_16x16x32_bf16 v[34:37], v[146:149], v[210:213], v[34:37]
	v_mfma_f32_16x16x32_bf16 v[34:37], v[150:153], v[214:217], v[34:37]
	v_mfma_f32_16x16x32_bf16 v[26:29], v[164:167], v[210:213], v[26:29]
	v_mfma_f32_16x16x32_bf16 v[26:29], v[168:171], v[214:217], v[26:29]
	v_mfma_f32_16x16x32_bf16 v[22:25], v[172:175], v[210:213], v[22:25]
	v_mfma_f32_16x16x32_bf16 v[22:25], v[176:179], v[214:217], v[22:25]
	v_mfma_f32_16x16x32_bf16 v[14:17], v[186:189], v[210:213], v[14:17]
	v_mfma_f32_16x16x32_bf16 v[14:17], v[190:193], v[214:217], v[14:17]
	v_mfma_f32_16x16x32_bf16 v[18:21], v[146:149], v[218:221], v[18:21]
	v_mfma_f32_16x16x32_bf16 v[18:21], v[150:153], v[222:225], v[18:21]
	v_mfma_f32_16x16x32_bf16 v[10:13], v[164:167], v[218:221], v[10:13]
	v_mfma_f32_16x16x32_bf16 v[10:13], v[168:171], v[222:225], v[10:13]
	v_mfma_f32_16x16x32_bf16 v[6:9], v[172:175], v[218:221], v[6:9]
	v_mfma_f32_16x16x32_bf16 v[6:9], v[176:179], v[222:225], v[6:9]
	v_mfma_f32_16x16x32_bf16 v[2:5], v[186:189], v[218:221], v[2:5]
	v_mfma_f32_16x16x32_bf16 v[2:5], v[190:193], v[222:225], v[2:5]
	s_setprio 0
	s_barrier
	s_add_i32 s79, 0, 0x18000
	s_add_i32 s82, 0, 0x1c000
	v_add_u32_e32 v168, s79, v155
	v_add_u32_e32 v183, s82, v155
	ds_read_b128 v[146:149], v168
	ds_read_b128 v[150:153], v168 offset:1024
	ds_read_b128 v[164:167], v168 offset:2048
	ds_read_b128 v[168:171], v168 offset:3072
	ds_read_b128 v[172:175], v183
	ds_read_b128 v[176:179], v183 offset:1024
	ds_read_b128 v[186:189], v183 offset:2048
	ds_read_b128 v[190:193], v183 offset:3072
	s_add_u32 s80, s90, 0x100000
	s_addc_u32 s81, s91, 0
	s_mov_b32 m0, s59
	ds_read_b128 v[194:197], v161 offset:32768
	ds_read_b128 v[198:201], v161 offset:33792
	ds_read_b128 v[202:205], v161 offset:34816
	ds_read_b128 v[206:209], v161 offset:35840
	ds_read_b128 v[210:213], v161 offset:36864
	ds_read_b128 v[214:217], v161 offset:37888
	ds_read_b128 v[218:221], v161 offset:38912
	ds_read_b128 v[222:225], v161 offset:39936
	global_load_lds_dwordx4 v130, s[80:81]
	s_mov_b32 m0, s62
	s_nop 0
	global_load_lds_dwordx4 v134, s[80:81]
	s_waitcnt vmcnt(8)
	s_waitcnt lgkmcnt(0)
	s_barrier
	s_setprio 1
	s_waitcnt lgkmcnt(0)
	v_mfma_f32_16x16x32_bf16 v[126:129], v[146:149], v[194:197], v[126:129]
	v_mfma_f32_16x16x32_bf16 v[126:129], v[150:153], v[198:201], v[126:129]
	v_mfma_f32_16x16x32_bf16 v[122:125], v[164:167], v[194:197], v[122:125]
	v_mfma_f32_16x16x32_bf16 v[122:125], v[168:171], v[198:201], v[122:125]
	v_mfma_f32_16x16x32_bf16 v[118:121], v[172:175], v[194:197], v[118:121]
	v_mfma_f32_16x16x32_bf16 v[118:121], v[176:179], v[198:201], v[118:121]
	v_mfma_f32_16x16x32_bf16 v[110:113], v[186:189], v[194:197], v[110:113]
	v_mfma_f32_16x16x32_bf16 v[110:113], v[190:193], v[198:201], v[110:113]
	v_mfma_f32_16x16x32_bf16 v[114:117], v[146:149], v[202:205], v[114:117]
	v_mfma_f32_16x16x32_bf16 v[114:117], v[150:153], v[206:209], v[114:117]
	v_mfma_f32_16x16x32_bf16 v[106:109], v[164:167], v[202:205], v[106:109]
	v_mfma_f32_16x16x32_bf16 v[106:109], v[168:171], v[206:209], v[106:109]
	v_mfma_f32_16x16x32_bf16 v[102:105], v[172:175], v[202:205], v[102:105]
	v_mfma_f32_16x16x32_bf16 v[102:105], v[176:179], v[206:209], v[102:105]
	v_mfma_f32_16x16x32_bf16 v[94:97], v[186:189], v[202:205], v[94:97]
	v_mfma_f32_16x16x32_bf16 v[94:97], v[190:193], v[206:209], v[94:97]
	v_mfma_f32_16x16x32_bf16 v[98:101], v[146:149], v[210:213], v[98:101]
	v_mfma_f32_16x16x32_bf16 v[98:101], v[150:153], v[214:217], v[98:101]
	v_mfma_f32_16x16x32_bf16 v[90:93], v[164:167], v[210:213], v[90:93]
	v_mfma_f32_16x16x32_bf16 v[90:93], v[168:171], v[214:217], v[90:93]
	v_mfma_f32_16x16x32_bf16 v[86:89], v[172:175], v[210:213], v[86:89]
	v_mfma_f32_16x16x32_bf16 v[86:89], v[176:179], v[214:217], v[86:89]
	v_mfma_f32_16x16x32_bf16 v[78:81], v[186:189], v[210:213], v[78:81]
	v_mfma_f32_16x16x32_bf16 v[78:81], v[190:193], v[214:217], v[78:81]
	v_mfma_f32_16x16x32_bf16 v[82:85], v[146:149], v[218:221], v[82:85]
	v_mfma_f32_16x16x32_bf16 v[82:85], v[150:153], v[222:225], v[82:85]
	v_mfma_f32_16x16x32_bf16 v[74:77], v[164:167], v[218:221], v[74:77]
	v_mfma_f32_16x16x32_bf16 v[74:77], v[168:171], v[222:225], v[74:77]
	v_mfma_f32_16x16x32_bf16 v[70:73], v[172:175], v[218:221], v[70:73]
	v_mfma_f32_16x16x32_bf16 v[70:73], v[176:179], v[222:225], v[70:73]
	v_mfma_f32_16x16x32_bf16 v[66:69], v[186:189], v[218:221], v[66:69]
	v_mfma_f32_16x16x32_bf16 v[66:69], v[190:193], v[222:225], v[66:69]
	s_setprio 0
	s_barrier
	s_add_i32 s79, s79, s25
	s_mov_b32 m0, s79
	ds_read_b128 v[194:197], v161 offset:49152
	ds_read_b128 v[198:201], v161 offset:50176
	ds_read_b128 v[202:205], v161 offset:51200
	ds_read_b128 v[206:209], v161 offset:52224
	ds_read_b128 v[210:213], v161 offset:53248
	ds_read_b128 v[214:217], v161 offset:54272
	ds_read_b128 v[218:221], v161 offset:55296
	ds_read_b128 v[222:225], v161 offset:56320
	global_load_lds_dwordx4 v132, s[98:99]
	s_add_i32 m0, s79, 0x2000
	s_add_u32 s80, s88, 0x100080
	s_addc_u32 s81, s89, 0
	s_add_i32 s79, s82, s25
	global_load_lds_dwordx4 v136, s[98:99]
	s_mov_b32 m0, s79
	s_nop 0
	global_load_lds_dwordx4 v132, s[80:81]
	s_add_i32 m0, s79, 0x2000
	s_nop 0
	global_load_lds_dwordx4 v136, s[80:81]
	s_mov_b32 m0, s66
	s_nop 0
	global_load_lds_dwordx4 v130, s[100:101]
	s_mov_b32 m0, s67
	s_nop 0
	global_load_lds_dwordx4 v134, s[100:101]
	s_waitcnt vmcnt(8)
	s_waitcnt lgkmcnt(0)
	s_barrier
	s_setprio 1
	s_waitcnt lgkmcnt(0)
	v_mfma_f32_16x16x32_bf16 v[62:65], v[146:149], v[194:197], v[62:65]
	v_mfma_f32_16x16x32_bf16 v[62:65], v[150:153], v[198:201], v[62:65]
	v_mfma_f32_16x16x32_bf16 v[58:61], v[164:167], v[194:197], v[58:61]
	v_mfma_f32_16x16x32_bf16 v[58:61], v[168:171], v[198:201], v[58:61]
	v_mfma_f32_16x16x32_bf16 v[54:57], v[172:175], v[194:197], v[54:57]
	v_mfma_f32_16x16x32_bf16 v[54:57], v[176:179], v[198:201], v[54:57]
	v_mfma_f32_16x16x32_bf16 v[46:49], v[186:189], v[194:197], v[46:49]
	v_mfma_f32_16x16x32_bf16 v[46:49], v[190:193], v[198:201], v[46:49]
	v_mfma_f32_16x16x32_bf16 v[50:53], v[146:149], v[202:205], v[50:53]
	v_mfma_f32_16x16x32_bf16 v[50:53], v[150:153], v[206:209], v[50:53]
	v_mfma_f32_16x16x32_bf16 v[42:45], v[164:167], v[202:205], v[42:45]
	v_mfma_f32_16x16x32_bf16 v[42:45], v[168:171], v[206:209], v[42:45]
	v_mfma_f32_16x16x32_bf16 v[38:41], v[172:175], v[202:205], v[38:41]
	v_mfma_f32_16x16x32_bf16 v[38:41], v[176:179], v[206:209], v[38:41]
	v_mfma_f32_16x16x32_bf16 v[30:33], v[186:189], v[202:205], v[30:33]
	v_mfma_f32_16x16x32_bf16 v[30:33], v[190:193], v[206:209], v[30:33]
	v_mfma_f32_16x16x32_bf16 v[34:37], v[146:149], v[210:213], v[34:37]
	v_mfma_f32_16x16x32_bf16 v[34:37], v[150:153], v[214:217], v[34:37]
	v_mfma_f32_16x16x32_bf16 v[26:29], v[164:167], v[210:213], v[26:29]
	v_mfma_f32_16x16x32_bf16 v[26:29], v[168:171], v[214:217], v[26:29]
	v_mfma_f32_16x16x32_bf16 v[22:25], v[172:175], v[210:213], v[22:25]
	v_mfma_f32_16x16x32_bf16 v[22:25], v[176:179], v[214:217], v[22:25]
	v_mfma_f32_16x16x32_bf16 v[14:17], v[186:189], v[210:213], v[14:17]
	v_mfma_f32_16x16x32_bf16 v[14:17], v[190:193], v[214:217], v[14:17]
	v_mfma_f32_16x16x32_bf16 v[18:21], v[146:149], v[218:221], v[18:21]
	v_mfma_f32_16x16x32_bf16 v[18:21], v[150:153], v[222:225], v[18:21]
	v_mfma_f32_16x16x32_bf16 v[10:13], v[164:167], v[218:221], v[10:13]
	v_mfma_f32_16x16x32_bf16 v[10:13], v[168:171], v[222:225], v[10:13]
	v_mfma_f32_16x16x32_bf16 v[6:9], v[172:175], v[218:221], v[6:9]
	v_mfma_f32_16x16x32_bf16 v[6:9], v[176:179], v[222:225], v[6:9]
	v_mfma_f32_16x16x32_bf16 v[2:5], v[186:189], v[218:221], v[2:5]
	v_mfma_f32_16x16x32_bf16 v[2:5], v[190:193], v[222:225], v[2:5]
	s_setprio 0
	s_barrier
	s_add_i32 s78, s78, 2
	s_add_u32 s6, s6, 0x100
	s_addc_u32 s7, s7, 0
	s_add_u32 s76, s76, 0x100
	s_addc_u32 s77, s77, 0
	s_cmp_gt_u32 s78, 61
	s_cbranch_scc0 .LBB0_1790
	s_and_b64 vcc, exec, s[40:41]
	s_cbranch_vccz .LBB0_1793
	s_barrier

.LBB0_2109:
	ds_read_b128 v[130:133], v155
	ds_read_b128 v[134:137], v155 offset:1024
	ds_read_b128 v[138:141], v155 offset:2048
	ds_read_b128 v[142:145], v155 offset:3072
	ds_read_b128 v[166:169], v176
	ds_read_b128 v[170:173], v176 offset:1024
	ds_read_b128 v[186:189], v176 offset:2048
	ds_read_b128 v[190:193], v176 offset:3072
	s_add_u32 s74, s50, 0xfff00080
	s_addc_u32 s75, s51, -1
	s_cmp_eq_u32 s73, 60
	s_cselect_b32 s85, s26, s75
	s_cselect_b32 s84, s45, s74
	s_cselect_b32 s83, s43, s72
	s_cselect_b32 s82, s70, s71
	s_add_i32 m0, s23, 0xc000
	ds_read_b128 v[194:197], v177
	ds_read_b128 v[198:201], v177 offset:1024
	ds_read_b128 v[202:205], v177 offset:2048
	ds_read_b128 v[206:209], v177 offset:3072
	ds_read_b128 v[210:213], v177 offset:4096
	ds_read_b128 v[214:217], v177 offset:5120
	ds_read_b128 v[218:221], v177 offset:6144
	ds_read_b128 v[222:225], v177 offset:7168
	global_load_lds_dwordx4 v158, s[50:51]
	s_add_i32 m0, s23, 0xe000
	s_nop 0
	global_load_lds_dwordx4 v160, s[50:51]
	s_waitcnt vmcnt(8)
	s_waitcnt lgkmcnt(0)
	s_barrier
	s_setprio 1
	s_waitcnt lgkmcnt(0)
	v_mfma_f32_16x16x32_bf16 v[126:129], v[130:133], v[194:197], v[126:129]
	v_mfma_f32_16x16x32_bf16 v[126:129], v[134:137], v[198:201], v[126:129]
	v_mfma_f32_16x16x32_bf16 v[122:125], v[138:141], v[194:197], v[122:125]
	v_mfma_f32_16x16x32_bf16 v[122:125], v[142:145], v[198:201], v[122:125]
	v_mfma_f32_16x16x32_bf16 v[118:121], v[166:169], v[194:197], v[118:121]
	v_mfma_f32_16x16x32_bf16 v[118:121], v[170:173], v[198:201], v[118:121]
	v_mfma_f32_16x16x32_bf16 v[114:117], v[186:189], v[194:197], v[114:117]
	v_mfma_f32_16x16x32_bf16 v[114:117], v[190:193], v[198:201], v[114:117]
	v_mfma_f32_16x16x32_bf16 v[110:113], v[130:133], v[202:205], v[110:113]
	v_mfma_f32_16x16x32_bf16 v[110:113], v[134:137], v[206:209], v[110:113]
	v_mfma_f32_16x16x32_bf16 v[106:109], v[138:141], v[202:205], v[106:109]
	v_mfma_f32_16x16x32_bf16 v[106:109], v[142:145], v[206:209], v[106:109]
	v_mfma_f32_16x16x32_bf16 v[102:105], v[166:169], v[202:205], v[102:105]
	v_mfma_f32_16x16x32_bf16 v[102:105], v[170:173], v[206:209], v[102:105]
	v_mfma_f32_16x16x32_bf16 v[98:101], v[186:189], v[202:205], v[98:101]
	v_mfma_f32_16x16x32_bf16 v[98:101], v[190:193], v[206:209], v[98:101]
	v_mfma_f32_16x16x32_bf16 v[94:97], v[130:133], v[210:213], v[94:97]
	v_mfma_f32_16x16x32_bf16 v[94:97], v[134:137], v[214:217], v[94:97]
	v_mfma_f32_16x16x32_bf16 v[90:93], v[138:141], v[210:213], v[90:93]
	v_mfma_f32_16x16x32_bf16 v[90:93], v[142:145], v[214:217], v[90:93]
	v_mfma_f32_16x16x32_bf16 v[86:89], v[166:169], v[210:213], v[86:89]
	v_mfma_f32_16x16x32_bf16 v[86:89], v[170:173], v[214:217], v[86:89]
	v_mfma_f32_16x16x32_bf16 v[82:85], v[186:189], v[210:213], v[82:85]
	v_mfma_f32_16x16x32_bf16 v[82:85], v[190:193], v[214:217], v[82:85]
	v_mfma_f32_16x16x32_bf16 v[78:81], v[130:133], v[218:221], v[78:81]
	v_mfma_f32_16x16x32_bf16 v[78:81], v[134:137], v[222:225], v[78:81]
	v_mfma_f32_16x16x32_bf16 v[74:77], v[138:141], v[218:221], v[74:77]
	v_mfma_f32_16x16x32_bf16 v[74:77], v[142:145], v[222:225], v[74:77]
	v_mfma_f32_16x16x32_bf16 v[70:73], v[166:169], v[218:221], v[70:73]
	v_mfma_f32_16x16x32_bf16 v[70:73], v[170:173], v[222:225], v[70:73]
	v_mfma_f32_16x16x32_bf16 v[66:69], v[186:189], v[218:221], v[66:69]
	v_mfma_f32_16x16x32_bf16 v[66:69], v[190:193], v[222:225], v[66:69]
	s_setprio 0
	s_barrier
	s_add_i32 s74, s67, s3
	s_add_u32 s98, s82, 0x80
	s_addc_u32 s99, s83, 0
	s_mov_b32 m0, s74
	ds_read_b128 v[194:197], v177 offset:16384
	ds_read_b128 v[198:201], v177 offset:17408
	ds_read_b128 v[202:205], v177 offset:18432
	ds_read_b128 v[206:209], v177 offset:19456
	ds_read_b128 v[210:213], v177 offset:20480
	ds_read_b128 v[214:217], v177 offset:21504
	ds_read_b128 v[218:221], v177 offset:22528
	ds_read_b128 v[222:225], v177 offset:23552
	global_load_lds_dwordx4 v148, s[82:83]
	s_add_i32 m0, s74, 0x2000
	s_add_u32 s74, s82, 0x100000
	s_addc_u32 s75, s83, 0
	s_add_i32 s76, s68, s3
	global_load_lds_dwordx4 v152, s[82:83]
	s_mov_b32 m0, s76
	global_load_lds_dwordx4 v148, s[74:75]
	s_add_i32 m0, s76, 0x2000
	s_nop 0
	global_load_lds_dwordx4 v152, s[74:75]
	s_add_u32 s100, s84, 0x80
	s_addc_u32 s101, s85, 0
	s_mov_b32 m0, s23
	s_nop 0
	global_load_lds_dwordx4 v146, s[84:85]
	s_mov_b32 m0, s25
	s_nop 0
	global_load_lds_dwordx4 v150, s[84:85]
	s_waitcnt vmcnt(8)
	s_waitcnt lgkmcnt(0)
	s_barrier
	s_setprio 1
	s_waitcnt lgkmcnt(0)
	v_mfma_f32_16x16x32_bf16 v[62:65], v[130:133], v[194:197], v[62:65]
	v_mfma_f32_16x16x32_bf16 v[62:65], v[134:137], v[198:201], v[62:65]
	v_mfma_f32_16x16x32_bf16 v[58:61], v[138:141], v[194:197], v[58:61]
	v_mfma_f32_16x16x32_bf16 v[58:61], v[142:145], v[198:201], v[58:61]
	v_mfma_f32_16x16x32_bf16 v[54:57], v[166:169], v[194:197], v[54:57]
	v_mfma_f32_16x16x32_bf16 v[54:57], v[170:173], v[198:201], v[54:57]
	v_mfma_f32_16x16x32_bf16 v[50:53], v[186:189], v[194:197], v[50:53]
	v_mfma_f32_16x16x32_bf16 v[50:53], v[190:193], v[198:201], v[50:53]
	v_mfma_f32_16x16x32_bf16 v[46:49], v[130:133], v[202:205], v[46:49]
	v_mfma_f32_16x16x32_bf16 v[46:49], v[134:137], v[206:209], v[46:49]
	v_mfma_f32_16x16x32_bf16 v[42:45], v[138:141], v[202:205], v[42:45]
	v_mfma_f32_16x16x32_bf16 v[42:45], v[142:145], v[206:209], v[42:45]
	v_mfma_f32_16x16x32_bf16 v[38:41], v[166:169], v[202:205], v[38:41]
	v_mfma_f32_16x16x32_bf16 v[38:41], v[170:173], v[206:209], v[38:41]
	v_mfma_f32_16x16x32_bf16 v[34:37], v[186:189], v[202:205], v[34:37]
	v_mfma_f32_16x16x32_bf16 v[34:37], v[190:193], v[206:209], v[34:37]
	v_mfma_f32_16x16x32_bf16 v[30:33], v[130:133], v[210:213], v[30:33]
	v_mfma_f32_16x16x32_bf16 v[30:33], v[134:137], v[214:217], v[30:33]
	v_mfma_f32_16x16x32_bf16 v[26:29], v[138:141], v[210:213], v[26:29]
	v_mfma_f32_16x16x32_bf16 v[26:29], v[142:145], v[214:217], v[26:29]
	v_mfma_f32_16x16x32_bf16 v[22:25], v[166:169], v[210:213], v[22:25]
	v_mfma_f32_16x16x32_bf16 v[22:25], v[170:173], v[214:217], v[22:25]
	v_mfma_f32_16x16x32_bf16 v[18:21], v[186:189], v[210:213], v[18:21]
	v_mfma_f32_16x16x32_bf16 v[18:21], v[190:193], v[214:217], v[18:21]
	v_mfma_f32_16x16x32_bf16 v[14:17], v[130:133], v[218:221], v[14:17]
	v_mfma_f32_16x16x32_bf16 v[14:17], v[134:137], v[222:225], v[14:17]
	v_mfma_f32_16x16x32_bf16 v[10:13], v[138:141], v[218:221], v[10:13]
	v_mfma_f32_16x16x32_bf16 v[10:13], v[142:145], v[222:225], v[10:13]
	v_mfma_f32_16x16x32_bf16 v[6:9], v[166:169], v[218:221], v[6:9]
	v_mfma_f32_16x16x32_bf16 v[6:9], v[170:173], v[222:225], v[6:9]
	v_mfma_f32_16x16x32_bf16 v[2:5], v[186:189], v[218:221], v[2:5]
	v_mfma_f32_16x16x32_bf16 v[2:5], v[190:193], v[222:225], v[2:5]
	s_setprio 0
	s_barrier
	s_add_i32 s76, 0, 0x18000
	s_add_i32 s77, 0, 0x1c000
	v_add_u32_e32 v142, s76, v174
	v_add_u32_e32 v179, s77, v174
	ds_read_b128 v[130:133], v142
	ds_read_b128 v[134:137], v142 offset:1024
	ds_read_b128 v[138:141], v142 offset:2048
	ds_read_b128 v[142:145], v142 offset:3072
	ds_read_b128 v[166:169], v179
	ds_read_b128 v[170:173], v179 offset:1024
	ds_read_b128 v[186:189], v179 offset:2048
	ds_read_b128 v[190:193], v179 offset:3072
	s_add_u32 s74, s84, 0x100000
	s_addc_u32 s75, s85, 0
	s_mov_b32 m0, s33
	ds_read_b128 v[194:197], v177 offset:32768
	ds_read_b128 v[198:201], v177 offset:33792
	ds_read_b128 v[202:205], v177 offset:34816
	ds_read_b128 v[206:209], v177 offset:35840
	ds_read_b128 v[210:213], v177 offset:36864
	ds_read_b128 v[214:217], v177 offset:37888
	ds_read_b128 v[218:221], v177 offset:38912
	ds_read_b128 v[222:225], v177 offset:39936
	global_load_lds_dwordx4 v146, s[74:75]
	s_mov_b32 m0, s35
	s_nop 0
	global_load_lds_dwordx4 v150, s[74:75]
	s_waitcnt vmcnt(8)
	s_waitcnt lgkmcnt(0)
	s_barrier
	s_setprio 1
	s_waitcnt lgkmcnt(0)
	v_mfma_f32_16x16x32_bf16 v[126:129], v[130:133], v[194:197], v[126:129]
	v_mfma_f32_16x16x32_bf16 v[126:129], v[134:137], v[198:201], v[126:129]
	v_mfma_f32_16x16x32_bf16 v[122:125], v[138:141], v[194:197], v[122:125]
	v_mfma_f32_16x16x32_bf16 v[122:125], v[142:145], v[198:201], v[122:125]
	v_mfma_f32_16x16x32_bf16 v[118:121], v[166:169], v[194:197], v[118:121]
	v_mfma_f32_16x16x32_bf16 v[118:121], v[170:173], v[198:201], v[118:121]
	v_mfma_f32_16x16x32_bf16 v[114:117], v[186:189], v[194:197], v[114:117]
	v_mfma_f32_16x16x32_bf16 v[114:117], v[190:193], v[198:201], v[114:117]
	v_mfma_f32_16x16x32_bf16 v[110:113], v[130:133], v[202:205], v[110:113]
	v_mfma_f32_16x16x32_bf16 v[110:113], v[134:137], v[206:209], v[110:113]
	v_mfma_f32_16x16x32_bf16 v[106:109], v[138:141], v[202:205], v[106:109]
	v_mfma_f32_16x16x32_bf16 v[106:109], v[142:145], v[206:209], v[106:109]
	v_mfma_f32_16x16x32_bf16 v[102:105], v[166:169], v[202:205], v[102:105]
	v_mfma_f32_16x16x32_bf16 v[102:105], v[170:173], v[206:209], v[102:105]
	v_mfma_f32_16x16x32_bf16 v[98:101], v[186:189], v[202:205], v[98:101]
	v_mfma_f32_16x16x32_bf16 v[98:101], v[190:193], v[206:209], v[98:101]
	v_mfma_f32_16x16x32_bf16 v[94:97], v[130:133], v[210:213], v[94:97]
	v_mfma_f32_16x16x32_bf16 v[94:97], v[134:137], v[214:217], v[94:97]
	v_mfma_f32_16x16x32_bf16 v[90:93], v[138:141], v[210:213], v[90:93]
	v_mfma_f32_16x16x32_bf16 v[90:93], v[142:145], v[214:217], v[90:93]
	v_mfma_f32_16x16x32_bf16 v[86:89], v[166:169], v[210:213], v[86:89]
	v_mfma_f32_16x16x32_bf16 v[86:89], v[170:173], v[214:217], v[86:89]
	v_mfma_f32_16x16x32_bf16 v[82:85], v[186:189], v[210:213], v[82:85]
	v_mfma_f32_16x16x32_bf16 v[82:85], v[190:193], v[214:217], v[82:85]
	v_mfma_f32_16x16x32_bf16 v[78:81], v[130:133], v[218:221], v[78:81]
	v_mfma_f32_16x16x32_bf16 v[78:81], v[134:137], v[222:225], v[78:81]
	v_mfma_f32_16x16x32_bf16 v[74:77], v[138:141], v[218:221], v[74:77]
	v_mfma_f32_16x16x32_bf16 v[74:77], v[142:145], v[222:225], v[74:77]
	v_mfma_f32_16x16x32_bf16 v[70:73], v[166:169], v[218:221], v[70:73]
	v_mfma_f32_16x16x32_bf16 v[70:73], v[170:173], v[222:225], v[70:73]
	v_mfma_f32_16x16x32_bf16 v[66:69], v[186:189], v[218:221], v[66:69]
	v_mfma_f32_16x16x32_bf16 v[66:69], v[190:193], v[222:225], v[66:69]
	s_setprio 0
	s_barrier
	s_add_i32 s74, s76, s3
	s_mov_b32 m0, s74
	ds_read_b128 v[194:197], v177 offset:49152
	ds_read_b128 v[198:201], v177 offset:50176
	ds_read_b128 v[202:205], v177 offset:51200
	ds_read_b128 v[206:209], v177 offset:52224
	ds_read_b128 v[210:213], v177 offset:53248
	ds_read_b128 v[214:217], v177 offset:54272
	ds_read_b128 v[218:221], v177 offset:55296
	ds_read_b128 v[222:225], v177 offset:56320
	global_load_lds_dwordx4 v148, s[98:99]
	s_add_i32 m0, s74, 0x2000
	s_add_u32 s74, s82, 0x100080
	s_addc_u32 s75, s83, 0
	s_add_i32 s76, s77, s3
	global_load_lds_dwordx4 v152, s[98:99]
	s_mov_b32 m0, s76
	s_nop 0
	global_load_lds_dwordx4 v148, s[74:75]
	s_add_i32 m0, s76, 0x2000
	s_nop 0
	global_load_lds_dwordx4 v152, s[74:75]
	s_mov_b32 m0, s62
	s_nop 0
	global_load_lds_dwordx4 v146, s[100:101]
	s_mov_b32 m0, s63
	s_nop 0
	global_load_lds_dwordx4 v150, s[100:101]
	s_waitcnt vmcnt(8)
	s_waitcnt lgkmcnt(0)
	s_barrier
	s_setprio 1
	s_waitcnt lgkmcnt(0)
	v_mfma_f32_16x16x32_bf16 v[62:65], v[130:133], v[194:197], v[62:65]
	v_mfma_f32_16x16x32_bf16 v[62:65], v[134:137], v[198:201], v[62:65]
	v_mfma_f32_16x16x32_bf16 v[58:61], v[138:141], v[194:197], v[58:61]
	v_mfma_f32_16x16x32_bf16 v[58:61], v[142:145], v[198:201], v[58:61]
	v_mfma_f32_16x16x32_bf16 v[54:57], v[166:169], v[194:197], v[54:57]
	v_mfma_f32_16x16x32_bf16 v[54:57], v[170:173], v[198:201], v[54:57]
	v_mfma_f32_16x16x32_bf16 v[50:53], v[186:189], v[194:197], v[50:53]
	v_mfma_f32_16x16x32_bf16 v[50:53], v[190:193], v[198:201], v[50:53]
	v_mfma_f32_16x16x32_bf16 v[46:49], v[130:133], v[202:205], v[46:49]
	v_mfma_f32_16x16x32_bf16 v[46:49], v[134:137], v[206:209], v[46:49]
	v_mfma_f32_16x16x32_bf16 v[42:45], v[138:141], v[202:205], v[42:45]
	v_mfma_f32_16x16x32_bf16 v[42:45], v[142:145], v[206:209], v[42:45]
	v_mfma_f32_16x16x32_bf16 v[38:41], v[166:169], v[202:205], v[38:41]
	v_mfma_f32_16x16x32_bf16 v[38:41], v[170:173], v[206:209], v[38:41]
	v_mfma_f32_16x16x32_bf16 v[34:37], v[186:189], v[202:205], v[34:37]
	v_mfma_f32_16x16x32_bf16 v[34:37], v[190:193], v[206:209], v[34:37]
	v_mfma_f32_16x16x32_bf16 v[30:33], v[130:133], v[210:213], v[30:33]
	v_mfma_f32_16x16x32_bf16 v[30:33], v[134:137], v[214:217], v[30:33]
	v_mfma_f32_16x16x32_bf16 v[26:29], v[138:141], v[210:213], v[26:29]
	v_mfma_f32_16x16x32_bf16 v[26:29], v[142:145], v[214:217], v[26:29]
	v_mfma_f32_16x16x32_bf16 v[22:25], v[166:169], v[210:213], v[22:25]
	v_mfma_f32_16x16x32_bf16 v[22:25], v[170:173], v[214:217], v[22:25]
	v_mfma_f32_16x16x32_bf16 v[18:21], v[186:189], v[210:213], v[18:21]
	v_mfma_f32_16x16x32_bf16 v[18:21], v[190:193], v[214:217], v[18:21]
	v_mfma_f32_16x16x32_bf16 v[14:17], v[130:133], v[218:221], v[14:17]
	v_mfma_f32_16x16x32_bf16 v[14:17], v[134:137], v[222:225], v[14:17]
	v_mfma_f32_16x16x32_bf16 v[10:13], v[138:141], v[218:221], v[10:13]
	v_mfma_f32_16x16x32_bf16 v[10:13], v[142:145], v[222:225], v[10:13]
	v_mfma_f32_16x16x32_bf16 v[6:9], v[166:169], v[218:221], v[6:9]
	v_mfma_f32_16x16x32_bf16 v[6:9], v[170:173], v[222:225], v[6:9]
	v_mfma_f32_16x16x32_bf16 v[2:5], v[186:189], v[218:221], v[2:5]
	v_mfma_f32_16x16x32_bf16 v[2:5], v[190:193], v[222:225], v[2:5]
	s_setprio 0
	s_barrier
	s_add_i32 s73, s73, 2
	s_add_u32 s50, s50, 0x100
	s_addc_u32 s51, s51, 0
	s_add_u32 s71, s71, 0x100
	s_addc_u32 s72, s72, 0
	s_cmp_gt_u32 s73, 61
	s_cbranch_scc0 .LBB0_2109
	s_and_b64 vcc, exec, s[40:41]
	s_cbranch_vccz .LBB0_2112
	s_barrier

.LBB0_2212:
	ds_read_b128 v[150:153], v162
	ds_read_b128 v[168:171], v162 offset:1024
	ds_read_b128 v[172:175], v162 offset:2048
	ds_read_b128 v[176:179], v162 offset:3072
	ds_read_b128 v[186:189], v163
	ds_read_b128 v[190:193], v163 offset:1024
	ds_read_b128 v[194:197], v163 offset:2048
	ds_read_b128 v[198:201], v163 offset:3072
	s_add_u32 s50, s6, 0xfff00080
	s_addc_u32 s51, s7, -1
	s_cmp_eq_u32 s79, 60
	s_cselect_b32 s81, s45, s51
	s_cselect_b32 s80, s75, s50
	s_cselect_b32 s51, s43, s78
	s_cselect_b32 s50, s76, s77
	s_add_i32 m0, s33, 0xc000
	ds_read_b128 v[202:205], v164
	ds_read_b128 v[206:209], v164 offset:1024
	ds_read_b128 v[210:213], v164 offset:2048
	ds_read_b128 v[214:217], v164 offset:3072
	ds_read_b128 v[218:221], v164 offset:4096
	ds_read_b128 v[222:225], v164 offset:5120
	ds_read_b128 v[226:229], v164 offset:6144
	ds_read_b128 v[230:233], v164 offset:7168
	global_load_lds_dwordx4 v142, s[6:7]
	s_add_i32 m0, s33, 0xe000
	s_nop 0
	global_load_lds_dwordx4 v144, s[6:7]
	s_waitcnt vmcnt(8)
	s_waitcnt lgkmcnt(0)
	s_barrier
	s_setprio 1
	s_waitcnt lgkmcnt(0)
	v_mfma_f32_16x16x32_bf16 v[126:129], v[150:153], v[202:205], v[126:129]
	v_mfma_f32_16x16x32_bf16 v[126:129], v[168:171], v[206:209], v[126:129]
	v_mfma_f32_16x16x32_bf16 v[118:121], v[172:175], v[202:205], v[118:121]
	v_mfma_f32_16x16x32_bf16 v[118:121], v[176:179], v[206:209], v[118:121]
	v_mfma_f32_16x16x32_bf16 v[122:125], v[186:189], v[202:205], v[122:125]
	v_mfma_f32_16x16x32_bf16 v[122:125], v[190:193], v[206:209], v[122:125]
	v_mfma_f32_16x16x32_bf16 v[114:117], v[194:197], v[202:205], v[114:117]
	v_mfma_f32_16x16x32_bf16 v[114:117], v[198:201], v[206:209], v[114:117]
	v_mfma_f32_16x16x32_bf16 v[110:113], v[150:153], v[210:213], v[110:113]
	v_mfma_f32_16x16x32_bf16 v[110:113], v[168:171], v[214:217], v[110:113]
	v_mfma_f32_16x16x32_bf16 v[102:105], v[172:175], v[210:213], v[102:105]
	v_mfma_f32_16x16x32_bf16 v[102:105], v[176:179], v[214:217], v[102:105]
	v_mfma_f32_16x16x32_bf16 v[106:109], v[186:189], v[210:213], v[106:109]
	v_mfma_f32_16x16x32_bf16 v[106:109], v[190:193], v[214:217], v[106:109]
	v_mfma_f32_16x16x32_bf16 v[98:101], v[194:197], v[210:213], v[98:101]
	v_mfma_f32_16x16x32_bf16 v[98:101], v[198:201], v[214:217], v[98:101]
	v_mfma_f32_16x16x32_bf16 v[94:97], v[150:153], v[218:221], v[94:97]
	v_mfma_f32_16x16x32_bf16 v[94:97], v[168:171], v[222:225], v[94:97]
	v_mfma_f32_16x16x32_bf16 v[86:89], v[172:175], v[218:221], v[86:89]
	v_mfma_f32_16x16x32_bf16 v[86:89], v[176:179], v[222:225], v[86:89]
	v_mfma_f32_16x16x32_bf16 v[90:93], v[186:189], v[218:221], v[90:93]
	v_mfma_f32_16x16x32_bf16 v[90:93], v[190:193], v[222:225], v[90:93]
	v_mfma_f32_16x16x32_bf16 v[82:85], v[194:197], v[218:221], v[82:85]
	v_mfma_f32_16x16x32_bf16 v[82:85], v[198:201], v[222:225], v[82:85]
	v_mfma_f32_16x16x32_bf16 v[78:81], v[150:153], v[226:229], v[78:81]
	v_mfma_f32_16x16x32_bf16 v[78:81], v[168:171], v[230:233], v[78:81]
	v_mfma_f32_16x16x32_bf16 v[70:73], v[172:175], v[226:229], v[70:73]
	v_mfma_f32_16x16x32_bf16 v[70:73], v[176:179], v[230:233], v[70:73]
	v_mfma_f32_16x16x32_bf16 v[74:77], v[186:189], v[226:229], v[74:77]
	v_mfma_f32_16x16x32_bf16 v[74:77], v[190:193], v[230:233], v[74:77]
	v_mfma_f32_16x16x32_bf16 v[66:69], v[194:197], v[226:229], v[66:69]
	v_mfma_f32_16x16x32_bf16 v[66:69], v[198:201], v[230:233], v[66:69]
	s_setprio 0
	s_barrier
	s_add_i32 s82, s68, s29
	s_add_u32 s98, s50, 0x80
	s_addc_u32 s99, s51, 0
	s_mov_b32 m0, s82
	ds_read_b128 v[202:205], v164 offset:16384
	ds_read_b128 v[206:209], v164 offset:17408
	ds_read_b128 v[210:213], v164 offset:18432
	ds_read_b128 v[214:217], v164 offset:19456
	ds_read_b128 v[218:221], v164 offset:20480
	ds_read_b128 v[222:225], v164 offset:21504
	ds_read_b128 v[226:229], v164 offset:22528
	ds_read_b128 v[230:233], v164 offset:23552
	global_load_lds_dwordx4 v134, s[50:51]
	s_add_i32 m0, s82, 0x2000
	s_add_u32 s82, s50, 0x100000
	s_addc_u32 s83, s51, 0
	s_add_i32 s84, s69, s29
	global_load_lds_dwordx4 v138, s[50:51]
	s_mov_b32 m0, s84
	global_load_lds_dwordx4 v134, s[82:83]
	s_add_i32 m0, s84, 0x2000
	s_nop 0
	global_load_lds_dwordx4 v138, s[82:83]
	s_add_u32 s100, s80, 0x80
	s_addc_u32 s101, s81, 0
	s_mov_b32 m0, s33
	s_nop 0
	global_load_lds_dwordx4 v132, s[80:81]
	s_mov_b32 m0, s35
	s_nop 0
	global_load_lds_dwordx4 v136, s[80:81]
	s_waitcnt vmcnt(8)
	s_waitcnt lgkmcnt(0)
	s_barrier
	s_setprio 1
	s_waitcnt lgkmcnt(0)
	v_mfma_f32_16x16x32_bf16 v[62:65], v[150:153], v[202:205], v[62:65]
	v_mfma_f32_16x16x32_bf16 v[62:65], v[168:171], v[206:209], v[62:65]
	v_mfma_f32_16x16x32_bf16 v[54:57], v[172:175], v[202:205], v[54:57]
	v_mfma_f32_16x16x32_bf16 v[54:57], v[176:179], v[206:209], v[54:57]
	v_mfma_f32_16x16x32_bf16 v[58:61], v[186:189], v[202:205], v[58:61]
	v_mfma_f32_16x16x32_bf16 v[58:61], v[190:193], v[206:209], v[58:61]
	v_mfma_f32_16x16x32_bf16 v[50:53], v[194:197], v[202:205], v[50:53]
	v_mfma_f32_16x16x32_bf16 v[50:53], v[198:201], v[206:209], v[50:53]
	v_mfma_f32_16x16x32_bf16 v[46:49], v[150:153], v[210:213], v[46:49]
	v_mfma_f32_16x16x32_bf16 v[46:49], v[168:171], v[214:217], v[46:49]
	v_mfma_f32_16x16x32_bf16 v[38:41], v[172:175], v[210:213], v[38:41]
	v_mfma_f32_16x16x32_bf16 v[38:41], v[176:179], v[214:217], v[38:41]
	v_mfma_f32_16x16x32_bf16 v[42:45], v[186:189], v[210:213], v[42:45]
	v_mfma_f32_16x16x32_bf16 v[42:45], v[190:193], v[214:217], v[42:45]
	v_mfma_f32_16x16x32_bf16 v[34:37], v[194:197], v[210:213], v[34:37]
	v_mfma_f32_16x16x32_bf16 v[34:37], v[198:201], v[214:217], v[34:37]
	v_mfma_f32_16x16x32_bf16 v[30:33], v[150:153], v[218:221], v[30:33]
	v_mfma_f32_16x16x32_bf16 v[30:33], v[168:171], v[222:225], v[30:33]
	v_mfma_f32_16x16x32_bf16 v[22:25], v[172:175], v[218:221], v[22:25]
	v_mfma_f32_16x16x32_bf16 v[22:25], v[176:179], v[222:225], v[22:25]
	v_mfma_f32_16x16x32_bf16 v[26:29], v[186:189], v[218:221], v[26:29]
	v_mfma_f32_16x16x32_bf16 v[26:29], v[190:193], v[222:225], v[26:29]
	v_mfma_f32_16x16x32_bf16 v[18:21], v[194:197], v[218:221], v[18:21]
	v_mfma_f32_16x16x32_bf16 v[18:21], v[198:201], v[222:225], v[18:21]
	v_mfma_f32_16x16x32_bf16 v[14:17], v[150:153], v[226:229], v[14:17]
	v_mfma_f32_16x16x32_bf16 v[14:17], v[168:171], v[230:233], v[14:17]
	v_mfma_f32_16x16x32_bf16 v[6:9], v[172:175], v[226:229], v[6:9]
	v_mfma_f32_16x16x32_bf16 v[6:9], v[176:179], v[230:233], v[6:9]
	v_mfma_f32_16x16x32_bf16 v[10:13], v[186:189], v[226:229], v[10:13]
	v_mfma_f32_16x16x32_bf16 v[10:13], v[190:193], v[230:233], v[10:13]
	v_mfma_f32_16x16x32_bf16 v[2:5], v[194:197], v[226:229], v[2:5]
	v_mfma_f32_16x16x32_bf16 v[2:5], v[198:201], v[230:233], v[2:5]
	s_setprio 0
	s_barrier
	s_add_i32 s82, 0, 0x18000
	v_add_u32_e32 v140, s82, v158
	s_add_i32 s83, 0, 0x1c000
	ds_read_b128 v[150:153], v140
	ds_read_b128 v[168:171], v140 offset:1024
	ds_read_b128 v[172:175], v140 offset:2048
	ds_read_b128 v[176:179], v140 offset:3072
	v_add_u32_e32 v140, s83, v158
	ds_read_b128 v[186:189], v140
	ds_read_b128 v[190:193], v140 offset:1024
	ds_read_b128 v[194:197], v140 offset:2048
	ds_read_b128 v[198:201], v140 offset:3072
	s_add_u32 s80, s80, 0x100000
	s_addc_u32 s81, s81, 0
	s_mov_b32 m0, s59
	ds_read_b128 v[202:205], v164 offset:32768
	ds_read_b128 v[206:209], v164 offset:33792
	ds_read_b128 v[210:213], v164 offset:34816
	ds_read_b128 v[214:217], v164 offset:35840
	ds_read_b128 v[218:221], v164 offset:36864
	ds_read_b128 v[222:225], v164 offset:37888
	ds_read_b128 v[226:229], v164 offset:38912
	ds_read_b128 v[230:233], v164 offset:39936
	global_load_lds_dwordx4 v132, s[80:81]
	s_mov_b32 m0, s62
	s_nop 0
	global_load_lds_dwordx4 v136, s[80:81]
	s_waitcnt vmcnt(8)
	s_waitcnt lgkmcnt(0)
	s_barrier
	s_setprio 1
	s_waitcnt lgkmcnt(0)
	v_mfma_f32_16x16x32_bf16 v[126:129], v[150:153], v[202:205], v[126:129]
	v_mfma_f32_16x16x32_bf16 v[126:129], v[168:171], v[206:209], v[126:129]
	v_mfma_f32_16x16x32_bf16 v[118:121], v[172:175], v[202:205], v[118:121]
	v_mfma_f32_16x16x32_bf16 v[118:121], v[176:179], v[206:209], v[118:121]
	v_mfma_f32_16x16x32_bf16 v[122:125], v[186:189], v[202:205], v[122:125]
	v_mfma_f32_16x16x32_bf16 v[122:125], v[190:193], v[206:209], v[122:125]
	v_mfma_f32_16x16x32_bf16 v[114:117], v[194:197], v[202:205], v[114:117]
	v_mfma_f32_16x16x32_bf16 v[114:117], v[198:201], v[206:209], v[114:117]
	v_mfma_f32_16x16x32_bf16 v[110:113], v[150:153], v[210:213], v[110:113]
	v_mfma_f32_16x16x32_bf16 v[110:113], v[168:171], v[214:217], v[110:113]
	v_mfma_f32_16x16x32_bf16 v[102:105], v[172:175], v[210:213], v[102:105]
	v_mfma_f32_16x16x32_bf16 v[102:105], v[176:179], v[214:217], v[102:105]
	v_mfma_f32_16x16x32_bf16 v[106:109], v[186:189], v[210:213], v[106:109]
	v_mfma_f32_16x16x32_bf16 v[106:109], v[190:193], v[214:217], v[106:109]
	v_mfma_f32_16x16x32_bf16 v[98:101], v[194:197], v[210:213], v[98:101]
	v_mfma_f32_16x16x32_bf16 v[98:101], v[198:201], v[214:217], v[98:101]
	v_mfma_f32_16x16x32_bf16 v[94:97], v[150:153], v[218:221], v[94:97]
	v_mfma_f32_16x16x32_bf16 v[94:97], v[168:171], v[222:225], v[94:97]
	v_mfma_f32_16x16x32_bf16 v[86:89], v[172:175], v[218:221], v[86:89]
	v_mfma_f32_16x16x32_bf16 v[86:89], v[176:179], v[222:225], v[86:89]
	v_mfma_f32_16x16x32_bf16 v[90:93], v[186:189], v[218:221], v[90:93]
	v_mfma_f32_16x16x32_bf16 v[90:93], v[190:193], v[222:225], v[90:93]
	v_mfma_f32_16x16x32_bf16 v[82:85], v[194:197], v[218:221], v[82:85]
	v_mfma_f32_16x16x32_bf16 v[82:85], v[198:201], v[222:225], v[82:85]
	v_mfma_f32_16x16x32_bf16 v[78:81], v[150:153], v[226:229], v[78:81]
	v_mfma_f32_16x16x32_bf16 v[78:81], v[168:171], v[230:233], v[78:81]
	v_mfma_f32_16x16x32_bf16 v[70:73], v[172:175], v[226:229], v[70:73]
	v_mfma_f32_16x16x32_bf16 v[70:73], v[176:179], v[230:233], v[70:73]
	v_mfma_f32_16x16x32_bf16 v[74:77], v[186:189], v[226:229], v[74:77]
	v_mfma_f32_16x16x32_bf16 v[74:77], v[190:193], v[230:233], v[74:77]
	v_mfma_f32_16x16x32_bf16 v[66:69], v[194:197], v[226:229], v[66:69]
	v_mfma_f32_16x16x32_bf16 v[66:69], v[198:201], v[230:233], v[66:69]
	s_setprio 0
	s_barrier
	s_add_i32 s80, s82, s29
	s_mov_b32 m0, s80
	ds_read_b128 v[202:205], v164 offset:49152
	ds_read_b128 v[206:209], v164 offset:50176
	ds_read_b128 v[210:213], v164 offset:51200
	ds_read_b128 v[214:217], v164 offset:52224
	ds_read_b128 v[218:221], v164 offset:53248
	ds_read_b128 v[222:225], v164 offset:54272
	ds_read_b128 v[226:229], v164 offset:55296
	ds_read_b128 v[230:233], v164 offset:56320
	global_load_lds_dwordx4 v134, s[98:99]
	s_add_i32 m0, s80, 0x2000
	s_add_u32 s50, s50, 0x100080
	s_addc_u32 s51, s51, 0
	s_add_i32 s80, s83, s29
	global_load_lds_dwordx4 v138, s[98:99]
	s_mov_b32 m0, s80
	s_nop 0
	global_load_lds_dwordx4 v134, s[50:51]
	s_add_i32 m0, s80, 0x2000
	s_nop 0
	global_load_lds_dwordx4 v138, s[50:51]
	s_mov_b32 m0, s65
	s_nop 0
	global_load_lds_dwordx4 v132, s[100:101]
	s_mov_b32 m0, s66
	s_nop 0
	global_load_lds_dwordx4 v136, s[100:101]
	s_waitcnt vmcnt(8)
	s_waitcnt lgkmcnt(0)
	s_barrier
	s_setprio 1
	s_waitcnt lgkmcnt(0)
	v_mfma_f32_16x16x32_bf16 v[62:65], v[150:153], v[202:205], v[62:65]
	v_mfma_f32_16x16x32_bf16 v[62:65], v[168:171], v[206:209], v[62:65]
	v_mfma_f32_16x16x32_bf16 v[54:57], v[172:175], v[202:205], v[54:57]
	v_mfma_f32_16x16x32_bf16 v[54:57], v[176:179], v[206:209], v[54:57]
	v_mfma_f32_16x16x32_bf16 v[58:61], v[186:189], v[202:205], v[58:61]
	v_mfma_f32_16x16x32_bf16 v[58:61], v[190:193], v[206:209], v[58:61]
	v_mfma_f32_16x16x32_bf16 v[50:53], v[194:197], v[202:205], v[50:53]
	v_mfma_f32_16x16x32_bf16 v[50:53], v[198:201], v[206:209], v[50:53]
	v_mfma_f32_16x16x32_bf16 v[46:49], v[150:153], v[210:213], v[46:49]
	v_mfma_f32_16x16x32_bf16 v[46:49], v[168:171], v[214:217], v[46:49]
	v_mfma_f32_16x16x32_bf16 v[38:41], v[172:175], v[210:213], v[38:41]
	v_mfma_f32_16x16x32_bf16 v[38:41], v[176:179], v[214:217], v[38:41]
	v_mfma_f32_16x16x32_bf16 v[42:45], v[186:189], v[210:213], v[42:45]
	v_mfma_f32_16x16x32_bf16 v[42:45], v[190:193], v[214:217], v[42:45]
	v_mfma_f32_16x16x32_bf16 v[34:37], v[194:197], v[210:213], v[34:37]
	v_mfma_f32_16x16x32_bf16 v[34:37], v[198:201], v[214:217], v[34:37]
	v_mfma_f32_16x16x32_bf16 v[30:33], v[150:153], v[218:221], v[30:33]
	v_mfma_f32_16x16x32_bf16 v[30:33], v[168:171], v[222:225], v[30:33]
	v_mfma_f32_16x16x32_bf16 v[22:25], v[172:175], v[218:221], v[22:25]
	v_mfma_f32_16x16x32_bf16 v[22:25], v[176:179], v[222:225], v[22:25]
	v_mfma_f32_16x16x32_bf16 v[26:29], v[186:189], v[218:221], v[26:29]
	v_mfma_f32_16x16x32_bf16 v[26:29], v[190:193], v[222:225], v[26:29]
	v_mfma_f32_16x16x32_bf16 v[18:21], v[194:197], v[218:221], v[18:21]
	v_mfma_f32_16x16x32_bf16 v[18:21], v[198:201], v[222:225], v[18:21]
	v_mfma_f32_16x16x32_bf16 v[14:17], v[150:153], v[226:229], v[14:17]
	v_mfma_f32_16x16x32_bf16 v[14:17], v[168:171], v[230:233], v[14:17]
	v_mfma_f32_16x16x32_bf16 v[6:9], v[172:175], v[226:229], v[6:9]
	v_mfma_f32_16x16x32_bf16 v[6:9], v[176:179], v[230:233], v[6:9]
	v_mfma_f32_16x16x32_bf16 v[10:13], v[186:189], v[226:229], v[10:13]
	v_mfma_f32_16x16x32_bf16 v[10:13], v[190:193], v[230:233], v[10:13]
	v_mfma_f32_16x16x32_bf16 v[2:5], v[194:197], v[226:229], v[2:5]
	v_mfma_f32_16x16x32_bf16 v[2:5], v[198:201], v[230:233], v[2:5]
	s_setprio 0
	s_barrier
	s_add_i32 s79, s79, 2
	s_add_u32 s6, s6, 0x100
	s_addc_u32 s7, s7, 0
	s_add_u32 s77, s77, 0x100
	s_addc_u32 s78, s78, 0
	s_cmp_gt_u32 s79, 61
	s_cbranch_scc0 .LBB0_2212
	s_and_b64 vcc, exec, s[40:41]
	s_cbranch_vccz .LBB0_2215
	s_barrier

.LBB0_2340:
	ds_read_b128 v[130:133], v163
	ds_read_b128 v[134:137], v163 offset:1024
	ds_read_b128 v[138:141], v163 offset:2048
	ds_read_b128 v[142:145], v163 offset:3072
	ds_read_b128 v[146:149], v190
	ds_read_b128 v[150:153], v190 offset:1024
	ds_read_b128 v[174:177], v190 offset:2048
	ds_read_b128 v[178:181], v190 offset:3072
	s_add_u32 s42, s40, 0xffd50080
	s_addc_u32 s43, s41, -1
	s_cmpk_eq_i32 s71, 0xa8
	s_cselect_b32 s45, s1, s43
	s_cselect_b32 s44, s0, s42
	s_cselect_b32 s43, s39, s70
	s_cselect_b32 s42, s38, s12
	s_add_i32 m0, s46, 0xc000
	ds_read_b128 v[186:189], v191
	ds_read_b128 v[194:197], v191 offset:1024
	ds_read_b128 v[198:201], v191 offset:2048
	ds_read_b128 v[202:205], v191 offset:3072
	ds_read_b128 v[206:209], v191 offset:4096
	ds_read_b128 v[210:213], v191 offset:5120
	ds_read_b128 v[214:217], v191 offset:6144
	ds_read_b128 v[218:221], v191 offset:7168
	global_load_lds_dwordx4 v166, s[40:41]
	s_add_i32 m0, s46, 0xe000
	s_nop 0
	global_load_lds_dwordx4 v168, s[40:41]
	s_waitcnt vmcnt(8)
	s_waitcnt lgkmcnt(0)
	s_barrier
	s_setprio 1
	s_waitcnt lgkmcnt(0)
	v_mfma_f32_16x16x32_bf16 v[126:129], v[130:133], v[186:189], v[126:129]
	v_mfma_f32_16x16x32_bf16 v[126:129], v[134:137], v[194:197], v[126:129]
	v_mfma_f32_16x16x32_bf16 v[122:125], v[138:141], v[186:189], v[122:125]
	v_mfma_f32_16x16x32_bf16 v[122:125], v[142:145], v[194:197], v[122:125]
	v_mfma_f32_16x16x32_bf16 v[118:121], v[146:149], v[186:189], v[118:121]
	v_mfma_f32_16x16x32_bf16 v[118:121], v[150:153], v[194:197], v[118:121]
	v_mfma_f32_16x16x32_bf16 v[114:117], v[174:177], v[186:189], v[114:117]
	v_mfma_f32_16x16x32_bf16 v[114:117], v[178:181], v[194:197], v[114:117]
	v_mfma_f32_16x16x32_bf16 v[110:113], v[130:133], v[198:201], v[110:113]
	v_mfma_f32_16x16x32_bf16 v[110:113], v[134:137], v[202:205], v[110:113]
	v_mfma_f32_16x16x32_bf16 v[106:109], v[138:141], v[198:201], v[106:109]
	v_mfma_f32_16x16x32_bf16 v[106:109], v[142:145], v[202:205], v[106:109]
	v_mfma_f32_16x16x32_bf16 v[102:105], v[146:149], v[198:201], v[102:105]
	v_mfma_f32_16x16x32_bf16 v[102:105], v[150:153], v[202:205], v[102:105]
	v_mfma_f32_16x16x32_bf16 v[98:101], v[174:177], v[198:201], v[98:101]
	v_mfma_f32_16x16x32_bf16 v[98:101], v[178:181], v[202:205], v[98:101]
	v_mfma_f32_16x16x32_bf16 v[94:97], v[130:133], v[206:209], v[94:97]
	v_mfma_f32_16x16x32_bf16 v[94:97], v[134:137], v[210:213], v[94:97]
	v_mfma_f32_16x16x32_bf16 v[90:93], v[138:141], v[206:209], v[90:93]
	v_mfma_f32_16x16x32_bf16 v[90:93], v[142:145], v[210:213], v[90:93]
	v_mfma_f32_16x16x32_bf16 v[86:89], v[146:149], v[206:209], v[86:89]
	v_mfma_f32_16x16x32_bf16 v[86:89], v[150:153], v[210:213], v[86:89]
	v_mfma_f32_16x16x32_bf16 v[82:85], v[174:177], v[206:209], v[82:85]
	v_mfma_f32_16x16x32_bf16 v[82:85], v[178:181], v[210:213], v[82:85]
	v_mfma_f32_16x16x32_bf16 v[78:81], v[130:133], v[214:217], v[78:81]
	v_mfma_f32_16x16x32_bf16 v[78:81], v[134:137], v[218:221], v[78:81]
	v_mfma_f32_16x16x32_bf16 v[74:77], v[138:141], v[214:217], v[74:77]
	v_mfma_f32_16x16x32_bf16 v[74:77], v[142:145], v[218:221], v[74:77]
	v_mfma_f32_16x16x32_bf16 v[70:73], v[146:149], v[214:217], v[70:73]
	v_mfma_f32_16x16x32_bf16 v[70:73], v[150:153], v[218:221], v[70:73]
	v_mfma_f32_16x16x32_bf16 v[66:69], v[174:177], v[214:217], v[66:69]
	v_mfma_f32_16x16x32_bf16 v[66:69], v[178:181], v[218:221], v[66:69]
	s_setprio 0
	s_barrier
	s_add_i32 s72, s65, s35
	s_add_u32 s98, s42, 0x80
	s_addc_u32 s99, s43, 0
	s_mov_b32 m0, s72
	ds_read_b128 v[186:189], v191 offset:16384
	ds_read_b128 v[194:197], v191 offset:17408
	ds_read_b128 v[198:201], v191 offset:18432
	ds_read_b128 v[202:205], v191 offset:19456
	ds_read_b128 v[206:209], v191 offset:20480
	ds_read_b128 v[210:213], v191 offset:21504
	ds_read_b128 v[214:217], v191 offset:22528
	ds_read_b128 v[218:221], v191 offset:23552
	global_load_lds_dwordx4 v156, s[42:43]
	s_add_i32 m0, s72, 0x2000
	s_add_u32 s72, s42, 0x2b0000
	s_addc_u32 s73, s43, 0
	s_add_i32 s74, s66, s35
	global_load_lds_dwordx4 v160, s[42:43]
	s_mov_b32 m0, s74
	global_load_lds_dwordx4 v156, s[72:73]
	s_add_i32 m0, s74, 0x2000
	s_nop 0
	global_load_lds_dwordx4 v160, s[72:73]
	s_add_u32 s100, s44, 0x80
	s_addc_u32 s101, s45, 0
	s_mov_b32 m0, s46
	s_nop 0
	global_load_lds_dwordx4 v154, s[44:45]
	s_mov_b32 m0, s47
	s_nop 0
	global_load_lds_dwordx4 v158, s[44:45]
	s_waitcnt vmcnt(8)
	s_waitcnt lgkmcnt(0)
	s_barrier
	s_setprio 1
	s_waitcnt lgkmcnt(0)
	v_mfma_f32_16x16x32_bf16 v[62:65], v[130:133], v[186:189], v[62:65]
	v_mfma_f32_16x16x32_bf16 v[62:65], v[134:137], v[194:197], v[62:65]
	v_mfma_f32_16x16x32_bf16 v[58:61], v[138:141], v[186:189], v[58:61]
	v_mfma_f32_16x16x32_bf16 v[58:61], v[142:145], v[194:197], v[58:61]
	v_mfma_f32_16x16x32_bf16 v[54:57], v[146:149], v[186:189], v[54:57]
	v_mfma_f32_16x16x32_bf16 v[54:57], v[150:153], v[194:197], v[54:57]
	v_mfma_f32_16x16x32_bf16 v[50:53], v[174:177], v[186:189], v[50:53]
	v_mfma_f32_16x16x32_bf16 v[50:53], v[178:181], v[194:197], v[50:53]
	v_mfma_f32_16x16x32_bf16 v[46:49], v[130:133], v[198:201], v[46:49]
	v_mfma_f32_16x16x32_bf16 v[46:49], v[134:137], v[202:205], v[46:49]
	v_mfma_f32_16x16x32_bf16 v[42:45], v[138:141], v[198:201], v[42:45]
	v_mfma_f32_16x16x32_bf16 v[42:45], v[142:145], v[202:205], v[42:45]
	v_mfma_f32_16x16x32_bf16 v[38:41], v[146:149], v[198:201], v[38:41]
	v_mfma_f32_16x16x32_bf16 v[38:41], v[150:153], v[202:205], v[38:41]
	v_mfma_f32_16x16x32_bf16 v[34:37], v[174:177], v[198:201], v[34:37]
	v_mfma_f32_16x16x32_bf16 v[34:37], v[178:181], v[202:205], v[34:37]
	v_mfma_f32_16x16x32_bf16 v[30:33], v[130:133], v[206:209], v[30:33]
	v_mfma_f32_16x16x32_bf16 v[30:33], v[134:137], v[210:213], v[30:33]
	v_mfma_f32_16x16x32_bf16 v[26:29], v[138:141], v[206:209], v[26:29]
	v_mfma_f32_16x16x32_bf16 v[26:29], v[142:145], v[210:213], v[26:29]
	v_mfma_f32_16x16x32_bf16 v[22:25], v[146:149], v[206:209], v[22:25]
	v_mfma_f32_16x16x32_bf16 v[22:25], v[150:153], v[210:213], v[22:25]
	v_mfma_f32_16x16x32_bf16 v[18:21], v[174:177], v[206:209], v[18:21]
	v_mfma_f32_16x16x32_bf16 v[18:21], v[178:181], v[210:213], v[18:21]
	v_mfma_f32_16x16x32_bf16 v[14:17], v[130:133], v[214:217], v[14:17]
	v_mfma_f32_16x16x32_bf16 v[14:17], v[134:137], v[218:221], v[14:17]
	v_mfma_f32_16x16x32_bf16 v[10:13], v[138:141], v[214:217], v[10:13]
	v_mfma_f32_16x16x32_bf16 v[10:13], v[142:145], v[218:221], v[10:13]
	v_mfma_f32_16x16x32_bf16 v[6:9], v[146:149], v[214:217], v[6:9]
	v_mfma_f32_16x16x32_bf16 v[6:9], v[150:153], v[218:221], v[6:9]
	v_mfma_f32_16x16x32_bf16 v[2:5], v[174:177], v[214:217], v[2:5]
	v_mfma_f32_16x16x32_bf16 v[2:5], v[178:181], v[218:221], v[2:5]
	s_setprio 0
	s_barrier
	s_add_i32 s72, 0, 0x18000
	s_add_i32 s73, 0, 0x1c000
	v_add_u32_e32 v142, s72, v183
	v_add_u32_e32 v178, s73, v183
	ds_read_b128 v[130:133], v142
	ds_read_b128 v[134:137], v142 offset:1024
	ds_read_b128 v[138:141], v142 offset:2048
	ds_read_b128 v[142:145], v142 offset:3072
	ds_read_b128 v[146:149], v178
	ds_read_b128 v[150:153], v178 offset:1024
	ds_read_b128 v[174:177], v178 offset:2048
	ds_read_b128 v[178:181], v178 offset:3072
	s_add_u32 s44, s44, 0x2b0000
	s_addc_u32 s45, s45, 0
	s_mov_b32 m0, s48
	ds_read_b128 v[186:189], v191 offset:32768
	ds_read_b128 v[194:197], v191 offset:33792
	ds_read_b128 v[198:201], v191 offset:34816
	ds_read_b128 v[202:205], v191 offset:35840
	ds_read_b128 v[206:209], v191 offset:36864
	ds_read_b128 v[210:213], v191 offset:37888
	ds_read_b128 v[214:217], v191 offset:38912
	ds_read_b128 v[218:221], v191 offset:39936
	global_load_lds_dwordx4 v154, s[44:45]
	s_mov_b32 m0, s49
	s_nop 0
	global_load_lds_dwordx4 v158, s[44:45]
	s_waitcnt vmcnt(8)
	s_waitcnt lgkmcnt(0)
	s_barrier
	s_setprio 1
	s_waitcnt lgkmcnt(0)
	v_mfma_f32_16x16x32_bf16 v[126:129], v[130:133], v[186:189], v[126:129]
	v_mfma_f32_16x16x32_bf16 v[126:129], v[134:137], v[194:197], v[126:129]
	v_mfma_f32_16x16x32_bf16 v[122:125], v[138:141], v[186:189], v[122:125]
	v_mfma_f32_16x16x32_bf16 v[122:125], v[142:145], v[194:197], v[122:125]
	v_mfma_f32_16x16x32_bf16 v[118:121], v[146:149], v[186:189], v[118:121]
	v_mfma_f32_16x16x32_bf16 v[118:121], v[150:153], v[194:197], v[118:121]
	v_mfma_f32_16x16x32_bf16 v[114:117], v[174:177], v[186:189], v[114:117]
	v_mfma_f32_16x16x32_bf16 v[114:117], v[178:181], v[194:197], v[114:117]
	v_mfma_f32_16x16x32_bf16 v[110:113], v[130:133], v[198:201], v[110:113]
	v_mfma_f32_16x16x32_bf16 v[110:113], v[134:137], v[202:205], v[110:113]
	v_mfma_f32_16x16x32_bf16 v[106:109], v[138:141], v[198:201], v[106:109]
	v_mfma_f32_16x16x32_bf16 v[106:109], v[142:145], v[202:205], v[106:109]
	v_mfma_f32_16x16x32_bf16 v[102:105], v[146:149], v[198:201], v[102:105]
	v_mfma_f32_16x16x32_bf16 v[102:105], v[150:153], v[202:205], v[102:105]
	v_mfma_f32_16x16x32_bf16 v[98:101], v[174:177], v[198:201], v[98:101]
	v_mfma_f32_16x16x32_bf16 v[98:101], v[178:181], v[202:205], v[98:101]
	v_mfma_f32_16x16x32_bf16 v[94:97], v[130:133], v[206:209], v[94:97]
	v_mfma_f32_16x16x32_bf16 v[94:97], v[134:137], v[210:213], v[94:97]
	v_mfma_f32_16x16x32_bf16 v[90:93], v[138:141], v[206:209], v[90:93]
	v_mfma_f32_16x16x32_bf16 v[90:93], v[142:145], v[210:213], v[90:93]
	v_mfma_f32_16x16x32_bf16 v[86:89], v[146:149], v[206:209], v[86:89]
	v_mfma_f32_16x16x32_bf16 v[86:89], v[150:153], v[210:213], v[86:89]
	v_mfma_f32_16x16x32_bf16 v[82:85], v[174:177], v[206:209], v[82:85]
	v_mfma_f32_16x16x32_bf16 v[82:85], v[178:181], v[210:213], v[82:85]
	v_mfma_f32_16x16x32_bf16 v[78:81], v[130:133], v[214:217], v[78:81]
	v_mfma_f32_16x16x32_bf16 v[78:81], v[134:137], v[218:221], v[78:81]
	v_mfma_f32_16x16x32_bf16 v[74:77], v[138:141], v[214:217], v[74:77]
	v_mfma_f32_16x16x32_bf16 v[74:77], v[142:145], v[218:221], v[74:77]
	v_mfma_f32_16x16x32_bf16 v[70:73], v[146:149], v[214:217], v[70:73]
	v_mfma_f32_16x16x32_bf16 v[70:73], v[150:153], v[218:221], v[70:73]
	v_mfma_f32_16x16x32_bf16 v[66:69], v[174:177], v[214:217], v[66:69]
	v_mfma_f32_16x16x32_bf16 v[66:69], v[178:181], v[218:221], v[66:69]
	s_setprio 0
	s_barrier
	s_add_i32 s44, s72, s35
	s_mov_b32 m0, s44
	ds_read_b128 v[186:189], v191 offset:49152
	ds_read_b128 v[194:197], v191 offset:50176
	ds_read_b128 v[198:201], v191 offset:51200
	ds_read_b128 v[202:205], v191 offset:52224
	ds_read_b128 v[206:209], v191 offset:53248
	ds_read_b128 v[210:213], v191 offset:54272
	ds_read_b128 v[214:217], v191 offset:55296
	ds_read_b128 v[218:221], v191 offset:56320
	global_load_lds_dwordx4 v156, s[98:99]
	s_add_i32 m0, s44, 0x2000
	s_add_u32 s42, s42, 0x2b0080
	s_addc_u32 s43, s43, 0
	s_add_i32 s44, s73, s35
	global_load_lds_dwordx4 v160, s[98:99]
	s_mov_b32 m0, s44
	s_nop 0
	global_load_lds_dwordx4 v156, s[42:43]
	s_add_i32 m0, s44, 0x2000
	s_nop 0
	global_load_lds_dwordx4 v160, s[42:43]
	s_mov_b32 m0, s51
	s_nop 0
	global_load_lds_dwordx4 v154, s[100:101]
	s_mov_b32 m0, s59
	s_nop 0
	global_load_lds_dwordx4 v158, s[100:101]
	s_waitcnt vmcnt(8)
	s_waitcnt lgkmcnt(0)
	s_barrier
	s_setprio 1
	s_waitcnt lgkmcnt(0)
	v_mfma_f32_16x16x32_bf16 v[62:65], v[130:133], v[186:189], v[62:65]
	v_mfma_f32_16x16x32_bf16 v[62:65], v[134:137], v[194:197], v[62:65]
	v_mfma_f32_16x16x32_bf16 v[58:61], v[138:141], v[186:189], v[58:61]
	v_mfma_f32_16x16x32_bf16 v[58:61], v[142:145], v[194:197], v[58:61]
	v_mfma_f32_16x16x32_bf16 v[54:57], v[146:149], v[186:189], v[54:57]
	v_mfma_f32_16x16x32_bf16 v[54:57], v[150:153], v[194:197], v[54:57]
	v_mfma_f32_16x16x32_bf16 v[50:53], v[174:177], v[186:189], v[50:53]
	v_mfma_f32_16x16x32_bf16 v[50:53], v[178:181], v[194:197], v[50:53]
	v_mfma_f32_16x16x32_bf16 v[46:49], v[130:133], v[198:201], v[46:49]
	v_mfma_f32_16x16x32_bf16 v[46:49], v[134:137], v[202:205], v[46:49]
	v_mfma_f32_16x16x32_bf16 v[42:45], v[138:141], v[198:201], v[42:45]
	v_mfma_f32_16x16x32_bf16 v[42:45], v[142:145], v[202:205], v[42:45]
	v_mfma_f32_16x16x32_bf16 v[38:41], v[146:149], v[198:201], v[38:41]
	v_mfma_f32_16x16x32_bf16 v[38:41], v[150:153], v[202:205], v[38:41]
	v_mfma_f32_16x16x32_bf16 v[34:37], v[174:177], v[198:201], v[34:37]
	v_mfma_f32_16x16x32_bf16 v[34:37], v[178:181], v[202:205], v[34:37]
	v_mfma_f32_16x16x32_bf16 v[30:33], v[130:133], v[206:209], v[30:33]
	v_mfma_f32_16x16x32_bf16 v[30:33], v[134:137], v[210:213], v[30:33]
	v_mfma_f32_16x16x32_bf16 v[26:29], v[138:141], v[206:209], v[26:29]
	v_mfma_f32_16x16x32_bf16 v[26:29], v[142:145], v[210:213], v[26:29]
	v_mfma_f32_16x16x32_bf16 v[22:25], v[146:149], v[206:209], v[22:25]
	v_mfma_f32_16x16x32_bf16 v[22:25], v[150:153], v[210:213], v[22:25]
	v_mfma_f32_16x16x32_bf16 v[18:21], v[174:177], v[206:209], v[18:21]
	v_mfma_f32_16x16x32_bf16 v[18:21], v[178:181], v[210:213], v[18:21]
	v_mfma_f32_16x16x32_bf16 v[14:17], v[130:133], v[214:217], v[14:17]
	v_mfma_f32_16x16x32_bf16 v[14:17], v[134:137], v[218:221], v[14:17]
	v_mfma_f32_16x16x32_bf16 v[10:13], v[138:141], v[214:217], v[10:13]
	v_mfma_f32_16x16x32_bf16 v[10:13], v[142:145], v[218:221], v[10:13]
	v_mfma_f32_16x16x32_bf16 v[6:9], v[146:149], v[214:217], v[6:9]
	v_mfma_f32_16x16x32_bf16 v[6:9], v[150:153], v[218:221], v[6:9]
	v_mfma_f32_16x16x32_bf16 v[2:5], v[174:177], v[214:217], v[2:5]
	v_mfma_f32_16x16x32_bf16 v[2:5], v[178:181], v[218:221], v[2:5]
	s_setprio 0
	s_barrier
	s_add_i32 s71, s71, 2
	s_add_u32 s40, s40, 0x100
	s_addc_u32 s41, s41, 0
	s_add_u32 s12, s12, 0x100
	s_addc_u32 s70, s70, 0
	s_cmpk_gt_u32 s71, 0xa9
	s_cbranch_scc0 .LBB0_2340
	s_and_b64 vcc, exec, s[36:37]
	s_cbranch_vccz .LBB0_2343
	s_barrier

.LBB0_2464:
	ds_read_b128 v[150:153], v167
	ds_read_b128 v[172:175], v167 offset:1024
	ds_read_b128 v[176:179], v167 offset:2048
	ds_read_b128 v[184:187], v167 offset:3072
	ds_read_b128 v[188:191], v168
	ds_read_b128 v[192:195], v168 offset:1024
	ds_read_b128 v[196:199], v168 offset:2048
	ds_read_b128 v[200:203], v168 offset:3072
	s_add_u32 s74, s6, 0xfff00080
	s_addc_u32 s75, s7, -1
	s_cmp_eq_u32 s87, 60
	s_cselect_b32 s77, s47, s75
	s_cselect_b32 s76, s83, s74
	s_cselect_b32 s75, s45, s86
	s_cselect_b32 s74, s84, s85
	s_add_i32 m0, s59, 0xc000
	ds_read_b128 v[204:207], v169
	ds_read_b128 v[208:211], v169 offset:1024
	ds_read_b128 v[212:215], v169 offset:2048
	ds_read_b128 v[216:219], v169 offset:3072
	ds_read_b128 v[220:223], v169 offset:4096
	ds_read_b128 v[224:227], v169 offset:5120
	ds_read_b128 v[228:231], v169 offset:6144
	ds_read_b128 v[232:235], v169 offset:7168
	global_load_lds_dwordx4 v142, s[6:7]
	s_add_i32 m0, s59, 0xe000
	s_nop 0
	global_load_lds_dwordx4 v144, s[6:7]
	s_waitcnt vmcnt(8)
	s_waitcnt lgkmcnt(0)
	s_barrier
	s_setprio 1
	s_waitcnt lgkmcnt(0)
	v_mfma_f32_16x16x32_bf16 v[126:129], v[150:153], v[204:207], v[126:129]
	v_mfma_f32_16x16x32_bf16 v[126:129], v[172:175], v[208:211], v[126:129]
	v_mfma_f32_16x16x32_bf16 v[122:125], v[176:179], v[204:207], v[122:125]
	v_mfma_f32_16x16x32_bf16 v[122:125], v[184:187], v[208:211], v[122:125]
	v_mfma_f32_16x16x32_bf16 v[118:121], v[188:191], v[204:207], v[118:121]
	v_mfma_f32_16x16x32_bf16 v[118:121], v[192:195], v[208:211], v[118:121]
	v_mfma_f32_16x16x32_bf16 v[114:117], v[196:199], v[204:207], v[114:117]
	v_mfma_f32_16x16x32_bf16 v[114:117], v[200:203], v[208:211], v[114:117]
	v_mfma_f32_16x16x32_bf16 v[110:113], v[150:153], v[212:215], v[110:113]
	v_mfma_f32_16x16x32_bf16 v[110:113], v[172:175], v[216:219], v[110:113]
	v_mfma_f32_16x16x32_bf16 v[106:109], v[176:179], v[212:215], v[106:109]
	v_mfma_f32_16x16x32_bf16 v[106:109], v[184:187], v[216:219], v[106:109]
	v_mfma_f32_16x16x32_bf16 v[102:105], v[188:191], v[212:215], v[102:105]
	v_mfma_f32_16x16x32_bf16 v[102:105], v[192:195], v[216:219], v[102:105]
	v_mfma_f32_16x16x32_bf16 v[98:101], v[196:199], v[212:215], v[98:101]
	v_mfma_f32_16x16x32_bf16 v[98:101], v[200:203], v[216:219], v[98:101]
	v_mfma_f32_16x16x32_bf16 v[94:97], v[150:153], v[220:223], v[94:97]
	v_mfma_f32_16x16x32_bf16 v[94:97], v[172:175], v[224:227], v[94:97]
	v_mfma_f32_16x16x32_bf16 v[90:93], v[176:179], v[220:223], v[90:93]
	v_mfma_f32_16x16x32_bf16 v[90:93], v[184:187], v[224:227], v[90:93]
	v_mfma_f32_16x16x32_bf16 v[86:89], v[188:191], v[220:223], v[86:89]
	v_mfma_f32_16x16x32_bf16 v[86:89], v[192:195], v[224:227], v[86:89]
	v_mfma_f32_16x16x32_bf16 v[82:85], v[196:199], v[220:223], v[82:85]
	v_mfma_f32_16x16x32_bf16 v[82:85], v[200:203], v[224:227], v[82:85]
	v_mfma_f32_16x16x32_bf16 v[78:81], v[150:153], v[228:231], v[78:81]
	v_mfma_f32_16x16x32_bf16 v[78:81], v[172:175], v[232:235], v[78:81]
	v_mfma_f32_16x16x32_bf16 v[74:77], v[176:179], v[228:231], v[74:77]
	v_mfma_f32_16x16x32_bf16 v[74:77], v[184:187], v[232:235], v[74:77]
	v_mfma_f32_16x16x32_bf16 v[70:73], v[188:191], v[228:231], v[70:73]
	v_mfma_f32_16x16x32_bf16 v[70:73], v[192:195], v[232:235], v[70:73]
	v_mfma_f32_16x16x32_bf16 v[66:69], v[196:199], v[228:231], v[66:69]
	v_mfma_f32_16x16x32_bf16 v[66:69], v[200:203], v[232:235], v[66:69]
	s_setprio 0
	s_barrier
	s_add_i32 s88, s70, s27
	s_add_u32 s98, s74, 0x80
	s_addc_u32 s99, s75, 0
	s_mov_b32 m0, s88
	ds_read_b128 v[204:207], v169 offset:16384
	ds_read_b128 v[208:211], v169 offset:17408
	ds_read_b128 v[212:215], v169 offset:18432
	ds_read_b128 v[216:219], v169 offset:19456
	ds_read_b128 v[220:223], v169 offset:20480
	ds_read_b128 v[224:227], v169 offset:21504
	ds_read_b128 v[228:231], v169 offset:22528
	ds_read_b128 v[232:235], v169 offset:23552
	global_load_lds_dwordx4 v132, s[74:75]
	s_add_i32 m0, s88, 0x2000
	s_add_u32 s88, s74, 0x100000
	s_addc_u32 s89, s75, 0
	s_add_i32 s90, s71, s27
	global_load_lds_dwordx4 v136, s[74:75]
	s_mov_b32 m0, s90
	global_load_lds_dwordx4 v132, s[88:89]
	s_add_i32 m0, s90, 0x2000
	s_nop 0
	global_load_lds_dwordx4 v136, s[88:89]
	s_add_u32 s100, s76, 0x80
	s_addc_u32 s101, s77, 0
	s_mov_b32 m0, s59
	s_nop 0
	global_load_lds_dwordx4 v130, s[76:77]
	s_mov_b32 m0, s62
	s_nop 0
	global_load_lds_dwordx4 v134, s[76:77]
	s_waitcnt vmcnt(8)
	s_waitcnt lgkmcnt(0)
	s_barrier
	s_setprio 1
	s_waitcnt lgkmcnt(0)
	v_mfma_f32_16x16x32_bf16 v[62:65], v[150:153], v[204:207], v[62:65]
	v_mfma_f32_16x16x32_bf16 v[62:65], v[172:175], v[208:211], v[62:65]
	v_mfma_f32_16x16x32_bf16 v[58:61], v[176:179], v[204:207], v[58:61]
	v_mfma_f32_16x16x32_bf16 v[58:61], v[184:187], v[208:211], v[58:61]
	v_mfma_f32_16x16x32_bf16 v[54:57], v[188:191], v[204:207], v[54:57]
	v_mfma_f32_16x16x32_bf16 v[54:57], v[192:195], v[208:211], v[54:57]
	v_mfma_f32_16x16x32_bf16 v[46:49], v[196:199], v[204:207], v[46:49]
	v_mfma_f32_16x16x32_bf16 v[46:49], v[200:203], v[208:211], v[46:49]
	v_mfma_f32_16x16x32_bf16 v[50:53], v[150:153], v[212:215], v[50:53]
	v_mfma_f32_16x16x32_bf16 v[50:53], v[172:175], v[216:219], v[50:53]
	v_mfma_f32_16x16x32_bf16 v[42:45], v[176:179], v[212:215], v[42:45]
	v_mfma_f32_16x16x32_bf16 v[42:45], v[184:187], v[216:219], v[42:45]
	v_mfma_f32_16x16x32_bf16 v[38:41], v[188:191], v[212:215], v[38:41]
	v_mfma_f32_16x16x32_bf16 v[38:41], v[192:195], v[216:219], v[38:41]
	v_mfma_f32_16x16x32_bf16 v[30:33], v[196:199], v[212:215], v[30:33]
	v_mfma_f32_16x16x32_bf16 v[30:33], v[200:203], v[216:219], v[30:33]
	v_mfma_f32_16x16x32_bf16 v[34:37], v[150:153], v[220:223], v[34:37]
	v_mfma_f32_16x16x32_bf16 v[34:37], v[172:175], v[224:227], v[34:37]
	v_mfma_f32_16x16x32_bf16 v[26:29], v[176:179], v[220:223], v[26:29]
	v_mfma_f32_16x16x32_bf16 v[26:29], v[184:187], v[224:227], v[26:29]
	v_mfma_f32_16x16x32_bf16 v[22:25], v[188:191], v[220:223], v[22:25]
	v_mfma_f32_16x16x32_bf16 v[22:25], v[192:195], v[224:227], v[22:25]
	v_mfma_f32_16x16x32_bf16 v[14:17], v[196:199], v[220:223], v[14:17]
	v_mfma_f32_16x16x32_bf16 v[14:17], v[200:203], v[224:227], v[14:17]
	v_mfma_f32_16x16x32_bf16 v[18:21], v[150:153], v[228:231], v[18:21]
	v_mfma_f32_16x16x32_bf16 v[18:21], v[172:175], v[232:235], v[18:21]
	v_mfma_f32_16x16x32_bf16 v[10:13], v[176:179], v[228:231], v[10:13]
	v_mfma_f32_16x16x32_bf16 v[10:13], v[184:187], v[232:235], v[10:13]
	v_mfma_f32_16x16x32_bf16 v[6:9], v[188:191], v[228:231], v[6:9]
	v_mfma_f32_16x16x32_bf16 v[6:9], v[192:195], v[232:235], v[6:9]
	v_mfma_f32_16x16x32_bf16 v[2:5], v[196:199], v[228:231], v[2:5]
	v_mfma_f32_16x16x32_bf16 v[2:5], v[200:203], v[232:235], v[2:5]
	s_setprio 0
	s_barrier
	s_add_i32 s88, 0, 0x18000
	v_add_u32_e32 v140, s88, v163
	s_add_i32 s89, 0, 0x1c000
	ds_read_b128 v[150:153], v140
	ds_read_b128 v[172:175], v140 offset:1024
	ds_read_b128 v[176:179], v140 offset:2048
	ds_read_b128 v[184:187], v140 offset:3072
	v_add_u32_e32 v140, s89, v163
	ds_read_b128 v[188:191], v140
	ds_read_b128 v[192:195], v140 offset:1024
	ds_read_b128 v[196:199], v140 offset:2048
	ds_read_b128 v[200:203], v140 offset:3072
	s_add_u32 s76, s76, 0x100000
	s_addc_u32 s77, s77, 0
	s_mov_b32 m0, s63
	ds_read_b128 v[204:207], v169 offset:32768
	ds_read_b128 v[208:211], v169 offset:33792
	ds_read_b128 v[212:215], v169 offset:34816
	ds_read_b128 v[216:219], v169 offset:35840
	ds_read_b128 v[220:223], v169 offset:36864
	ds_read_b128 v[224:227], v169 offset:37888
	ds_read_b128 v[228:231], v169 offset:38912
	ds_read_b128 v[232:235], v169 offset:39936
	global_load_lds_dwordx4 v130, s[76:77]
	s_mov_b32 m0, s65
	s_nop 0
	global_load_lds_dwordx4 v134, s[76:77]
	s_waitcnt vmcnt(8)
	s_waitcnt lgkmcnt(0)
	s_barrier
	s_setprio 1
	s_waitcnt lgkmcnt(0)
	v_mfma_f32_16x16x32_bf16 v[126:129], v[150:153], v[204:207], v[126:129]
	v_mfma_f32_16x16x32_bf16 v[126:129], v[172:175], v[208:211], v[126:129]
	v_mfma_f32_16x16x32_bf16 v[122:125], v[176:179], v[204:207], v[122:125]
	v_mfma_f32_16x16x32_bf16 v[122:125], v[184:187], v[208:211], v[122:125]
	v_mfma_f32_16x16x32_bf16 v[118:121], v[188:191], v[204:207], v[118:121]
	v_mfma_f32_16x16x32_bf16 v[118:121], v[192:195], v[208:211], v[118:121]
	v_mfma_f32_16x16x32_bf16 v[114:117], v[196:199], v[204:207], v[114:117]
	v_mfma_f32_16x16x32_bf16 v[114:117], v[200:203], v[208:211], v[114:117]
	v_mfma_f32_16x16x32_bf16 v[110:113], v[150:153], v[212:215], v[110:113]
	v_mfma_f32_16x16x32_bf16 v[110:113], v[172:175], v[216:219], v[110:113]
	v_mfma_f32_16x16x32_bf16 v[106:109], v[176:179], v[212:215], v[106:109]
	v_mfma_f32_16x16x32_bf16 v[106:109], v[184:187], v[216:219], v[106:109]
	v_mfma_f32_16x16x32_bf16 v[102:105], v[188:191], v[212:215], v[102:105]
	v_mfma_f32_16x16x32_bf16 v[102:105], v[192:195], v[216:219], v[102:105]
	v_mfma_f32_16x16x32_bf16 v[98:101], v[196:199], v[212:215], v[98:101]
	v_mfma_f32_16x16x32_bf16 v[98:101], v[200:203], v[216:219], v[98:101]
	v_mfma_f32_16x16x32_bf16 v[94:97], v[150:153], v[220:223], v[94:97]
	v_mfma_f32_16x16x32_bf16 v[94:97], v[172:175], v[224:227], v[94:97]
	v_mfma_f32_16x16x32_bf16 v[90:93], v[176:179], v[220:223], v[90:93]
	v_mfma_f32_16x16x32_bf16 v[90:93], v[184:187], v[224:227], v[90:93]
	v_mfma_f32_16x16x32_bf16 v[86:89], v[188:191], v[220:223], v[86:89]
	v_mfma_f32_16x16x32_bf16 v[86:89], v[192:195], v[224:227], v[86:89]
	v_mfma_f32_16x16x32_bf16 v[82:85], v[196:199], v[220:223], v[82:85]
	v_mfma_f32_16x16x32_bf16 v[82:85], v[200:203], v[224:227], v[82:85]
	v_mfma_f32_16x16x32_bf16 v[78:81], v[150:153], v[228:231], v[78:81]
	v_mfma_f32_16x16x32_bf16 v[78:81], v[172:175], v[232:235], v[78:81]
	v_mfma_f32_16x16x32_bf16 v[74:77], v[176:179], v[228:231], v[74:77]
	v_mfma_f32_16x16x32_bf16 v[74:77], v[184:187], v[232:235], v[74:77]
	v_mfma_f32_16x16x32_bf16 v[70:73], v[188:191], v[228:231], v[70:73]
	v_mfma_f32_16x16x32_bf16 v[70:73], v[192:195], v[232:235], v[70:73]
	v_mfma_f32_16x16x32_bf16 v[66:69], v[196:199], v[228:231], v[66:69]
	v_mfma_f32_16x16x32_bf16 v[66:69], v[200:203], v[232:235], v[66:69]
	s_setprio 0
	s_barrier
	s_add_i32 s76, s88, s27
	s_mov_b32 m0, s76
	ds_read_b128 v[204:207], v169 offset:49152
	ds_read_b128 v[208:211], v169 offset:50176
	ds_read_b128 v[212:215], v169 offset:51200
	ds_read_b128 v[216:219], v169 offset:52224
	ds_read_b128 v[220:223], v169 offset:53248
	ds_read_b128 v[224:227], v169 offset:54272
	ds_read_b128 v[228:231], v169 offset:55296
	ds_read_b128 v[232:235], v169 offset:56320
	global_load_lds_dwordx4 v132, s[98:99]
	s_add_i32 m0, s76, 0x2000
	s_add_u32 s74, s74, 0x100080
	s_addc_u32 s75, s75, 0
	s_add_i32 s76, s89, s27
	global_load_lds_dwordx4 v136, s[98:99]
	s_mov_b32 m0, s76
	s_nop 0
	global_load_lds_dwordx4 v132, s[74:75]
	s_add_i32 m0, s76, 0x2000
	s_nop 0
	global_load_lds_dwordx4 v136, s[74:75]
	s_mov_b32 m0, s67
	s_nop 0
	global_load_lds_dwordx4 v130, s[100:101]
	s_mov_b32 m0, s68
	s_nop 0
	global_load_lds_dwordx4 v134, s[100:101]
	s_waitcnt vmcnt(8)
	s_waitcnt lgkmcnt(0)
	s_barrier
	s_setprio 1
	s_waitcnt lgkmcnt(0)
	v_mfma_f32_16x16x32_bf16 v[62:65], v[150:153], v[204:207], v[62:65]
	v_mfma_f32_16x16x32_bf16 v[62:65], v[172:175], v[208:211], v[62:65]
	v_mfma_f32_16x16x32_bf16 v[58:61], v[176:179], v[204:207], v[58:61]
	v_mfma_f32_16x16x32_bf16 v[58:61], v[184:187], v[208:211], v[58:61]
	v_mfma_f32_16x16x32_bf16 v[54:57], v[188:191], v[204:207], v[54:57]
	v_mfma_f32_16x16x32_bf16 v[54:57], v[192:195], v[208:211], v[54:57]
	v_mfma_f32_16x16x32_bf16 v[46:49], v[196:199], v[204:207], v[46:49]
	v_mfma_f32_16x16x32_bf16 v[46:49], v[200:203], v[208:211], v[46:49]
	v_mfma_f32_16x16x32_bf16 v[50:53], v[150:153], v[212:215], v[50:53]
	v_mfma_f32_16x16x32_bf16 v[50:53], v[172:175], v[216:219], v[50:53]
	v_mfma_f32_16x16x32_bf16 v[42:45], v[176:179], v[212:215], v[42:45]
	v_mfma_f32_16x16x32_bf16 v[42:45], v[184:187], v[216:219], v[42:45]
	v_mfma_f32_16x16x32_bf16 v[38:41], v[188:191], v[212:215], v[38:41]
	v_mfma_f32_16x16x32_bf16 v[38:41], v[192:195], v[216:219], v[38:41]
	v_mfma_f32_16x16x32_bf16 v[30:33], v[196:199], v[212:215], v[30:33]
	v_mfma_f32_16x16x32_bf16 v[30:33], v[200:203], v[216:219], v[30:33]
	v_mfma_f32_16x16x32_bf16 v[34:37], v[150:153], v[220:223], v[34:37]
	v_mfma_f32_16x16x32_bf16 v[34:37], v[172:175], v[224:227], v[34:37]
	v_mfma_f32_16x16x32_bf16 v[26:29], v[176:179], v[220:223], v[26:29]
	v_mfma_f32_16x16x32_bf16 v[26:29], v[184:187], v[224:227], v[26:29]
	v_mfma_f32_16x16x32_bf16 v[22:25], v[188:191], v[220:223], v[22:25]
	v_mfma_f32_16x16x32_bf16 v[22:25], v[192:195], v[224:227], v[22:25]
	v_mfma_f32_16x16x32_bf16 v[14:17], v[196:199], v[220:223], v[14:17]
	v_mfma_f32_16x16x32_bf16 v[14:17], v[200:203], v[224:227], v[14:17]
	v_mfma_f32_16x16x32_bf16 v[18:21], v[150:153], v[228:231], v[18:21]
	v_mfma_f32_16x16x32_bf16 v[18:21], v[172:175], v[232:235], v[18:21]
	v_mfma_f32_16x16x32_bf16 v[10:13], v[176:179], v[228:231], v[10:13]
	v_mfma_f32_16x16x32_bf16 v[10:13], v[184:187], v[232:235], v[10:13]
	v_mfma_f32_16x16x32_bf16 v[6:9], v[188:191], v[228:231], v[6:9]
	v_mfma_f32_16x16x32_bf16 v[6:9], v[192:195], v[232:235], v[6:9]
	v_mfma_f32_16x16x32_bf16 v[2:5], v[196:199], v[228:231], v[2:5]
	v_mfma_f32_16x16x32_bf16 v[2:5], v[200:203], v[232:235], v[2:5]
	s_setprio 0
	s_barrier
	s_add_i32 s87, s87, 2
	s_add_u32 s6, s6, 0x100
	s_addc_u32 s7, s7, 0
	s_add_u32 s85, s85, 0x100
	s_addc_u32 s86, s86, 0
	s_cmp_gt_u32 s87, 61
	s_cbranch_scc0 .LBB0_2464
	s_and_b64 vcc, exec, s[38:39]
	s_cbranch_vccz .LBB0_2467
	s_barrier

.LBB0_2494:
	ds_read_b128 v[160:163], v155
	ds_read_b128 v[164:167], v155 offset:1024
	ds_read_b128 v[168:171], v155 offset:2048
	ds_read_b128 v[172:175], v155 offset:3072
	ds_read_b128 v[176:179], v156
	ds_read_b128 v[184:187], v156 offset:1024
	ds_read_b128 v[188:191], v156 offset:2048
	ds_read_b128 v[192:195], v156 offset:3072
	s_add_u32 s48, s6, 0xfff00080
	s_addc_u32 s49, s7, -1
	s_cmp_eq_u32 s89, 60
	s_cselect_b32 s51, s43, s49
	s_cselect_b32 s50, s85, s48
	s_cselect_b32 s49, s41, s88
	s_cselect_b32 s48, s86, s87
	s_add_i32 m0, s63, 0xc000
	ds_read_b128 v[196:199], v157
	ds_read_b128 v[200:203], v157 offset:1024
	ds_read_b128 v[204:207], v157 offset:2048
	ds_read_b128 v[208:211], v157 offset:3072
	ds_read_b128 v[212:215], v157 offset:4096
	ds_read_b128 v[216:219], v157 offset:5120
	ds_read_b128 v[220:223], v157 offset:6144
	ds_read_b128 v[224:227], v157 offset:7168
	global_load_lds_dwordx4 v140, s[6:7]
	s_add_i32 m0, s63, 0xe000
	s_nop 0
	global_load_lds_dwordx4 v142, s[6:7]
	s_waitcnt vmcnt(8)
	s_waitcnt lgkmcnt(0)
	s_barrier
	s_setprio 1
	s_waitcnt lgkmcnt(0)
	v_mfma_f32_16x16x32_bf16 v[126:129], v[160:163], v[196:199], v[126:129]
	v_mfma_f32_16x16x32_bf16 v[126:129], v[164:167], v[200:203], v[126:129]
	v_mfma_f32_16x16x32_bf16 v[122:125], v[168:171], v[196:199], v[122:125]
	v_mfma_f32_16x16x32_bf16 v[122:125], v[172:175], v[200:203], v[122:125]
	v_mfma_f32_16x16x32_bf16 v[118:121], v[176:179], v[196:199], v[118:121]
	v_mfma_f32_16x16x32_bf16 v[118:121], v[184:187], v[200:203], v[118:121]
	v_mfma_f32_16x16x32_bf16 v[114:117], v[188:191], v[196:199], v[114:117]
	v_mfma_f32_16x16x32_bf16 v[114:117], v[192:195], v[200:203], v[114:117]
	v_mfma_f32_16x16x32_bf16 v[110:113], v[160:163], v[204:207], v[110:113]
	v_mfma_f32_16x16x32_bf16 v[110:113], v[164:167], v[208:211], v[110:113]
	v_mfma_f32_16x16x32_bf16 v[106:109], v[168:171], v[204:207], v[106:109]
	v_mfma_f32_16x16x32_bf16 v[106:109], v[172:175], v[208:211], v[106:109]
	v_mfma_f32_16x16x32_bf16 v[102:105], v[176:179], v[204:207], v[102:105]
	v_mfma_f32_16x16x32_bf16 v[102:105], v[184:187], v[208:211], v[102:105]
	v_mfma_f32_16x16x32_bf16 v[98:101], v[188:191], v[204:207], v[98:101]
	v_mfma_f32_16x16x32_bf16 v[98:101], v[192:195], v[208:211], v[98:101]
	v_mfma_f32_16x16x32_bf16 v[94:97], v[160:163], v[212:215], v[94:97]
	v_mfma_f32_16x16x32_bf16 v[94:97], v[164:167], v[216:219], v[94:97]
	v_mfma_f32_16x16x32_bf16 v[90:93], v[168:171], v[212:215], v[90:93]
	v_mfma_f32_16x16x32_bf16 v[90:93], v[172:175], v[216:219], v[90:93]
	v_mfma_f32_16x16x32_bf16 v[86:89], v[176:179], v[212:215], v[86:89]
	v_mfma_f32_16x16x32_bf16 v[86:89], v[184:187], v[216:219], v[86:89]
	v_mfma_f32_16x16x32_bf16 v[82:85], v[188:191], v[212:215], v[82:85]
	v_mfma_f32_16x16x32_bf16 v[82:85], v[192:195], v[216:219], v[82:85]
	v_mfma_f32_16x16x32_bf16 v[78:81], v[160:163], v[220:223], v[78:81]
	v_mfma_f32_16x16x32_bf16 v[78:81], v[164:167], v[224:227], v[78:81]
	v_mfma_f32_16x16x32_bf16 v[74:77], v[168:171], v[220:223], v[74:77]
	v_mfma_f32_16x16x32_bf16 v[74:77], v[172:175], v[224:227], v[74:77]
	v_mfma_f32_16x16x32_bf16 v[70:73], v[176:179], v[220:223], v[70:73]
	v_mfma_f32_16x16x32_bf16 v[70:73], v[184:187], v[224:227], v[70:73]
	v_mfma_f32_16x16x32_bf16 v[66:69], v[188:191], v[220:223], v[66:69]
	v_mfma_f32_16x16x32_bf16 v[66:69], v[192:195], v[224:227], v[66:69]
	s_setprio 0
	s_barrier
	s_add_i32 s90, s73, s27
	s_add_u32 s98, s48, 0x80
	s_addc_u32 s99, s49, 0
	s_mov_b32 m0, s90
	ds_read_b128 v[196:199], v157 offset:16384
	ds_read_b128 v[200:203], v157 offset:17408
	ds_read_b128 v[204:207], v157 offset:18432
	ds_read_b128 v[208:211], v157 offset:19456
	ds_read_b128 v[212:215], v157 offset:20480
	ds_read_b128 v[216:219], v157 offset:21504
	ds_read_b128 v[220:223], v157 offset:22528
	ds_read_b128 v[224:227], v157 offset:23552
	global_load_lds_dwordx4 v132, s[48:49]
	s_add_i32 m0, s90, 0x2000
	s_add_u32 s90, s48, 0x100000
	s_addc_u32 s91, s49, 0
	s_add_i32 s92, s74, s27
	global_load_lds_dwordx4 v136, s[48:49]
	s_mov_b32 m0, s92
	global_load_lds_dwordx4 v132, s[90:91]
	s_add_i32 m0, s92, 0x2000
	s_nop 0
	global_load_lds_dwordx4 v136, s[90:91]
	s_add_u32 s100, s50, 0x80
	s_addc_u32 s101, s51, 0
	s_mov_b32 m0, s63
	s_nop 0
	global_load_lds_dwordx4 v130, s[50:51]
	s_mov_b32 m0, s65
	s_nop 0
	global_load_lds_dwordx4 v134, s[50:51]
	s_waitcnt vmcnt(8)
	s_waitcnt lgkmcnt(0)
	s_barrier
	s_setprio 1
	s_waitcnt lgkmcnt(0)
	v_mfma_f32_16x16x32_bf16 v[62:65], v[160:163], v[196:199], v[62:65]
	v_mfma_f32_16x16x32_bf16 v[62:65], v[164:167], v[200:203], v[62:65]
	v_mfma_f32_16x16x32_bf16 v[58:61], v[168:171], v[196:199], v[58:61]
	v_mfma_f32_16x16x32_bf16 v[58:61], v[172:175], v[200:203], v[58:61]
	v_mfma_f32_16x16x32_bf16 v[54:57], v[176:179], v[196:199], v[54:57]
	v_mfma_f32_16x16x32_bf16 v[54:57], v[184:187], v[200:203], v[54:57]
	v_mfma_f32_16x16x32_bf16 v[46:49], v[188:191], v[196:199], v[46:49]
	v_mfma_f32_16x16x32_bf16 v[46:49], v[192:195], v[200:203], v[46:49]
	v_mfma_f32_16x16x32_bf16 v[50:53], v[160:163], v[204:207], v[50:53]
	v_mfma_f32_16x16x32_bf16 v[50:53], v[164:167], v[208:211], v[50:53]
	v_mfma_f32_16x16x32_bf16 v[42:45], v[168:171], v[204:207], v[42:45]
	v_mfma_f32_16x16x32_bf16 v[42:45], v[172:175], v[208:211], v[42:45]
	v_mfma_f32_16x16x32_bf16 v[38:41], v[176:179], v[204:207], v[38:41]
	v_mfma_f32_16x16x32_bf16 v[38:41], v[184:187], v[208:211], v[38:41]
	v_mfma_f32_16x16x32_bf16 v[30:33], v[188:191], v[204:207], v[30:33]
	v_mfma_f32_16x16x32_bf16 v[30:33], v[192:195], v[208:211], v[30:33]
	v_mfma_f32_16x16x32_bf16 v[34:37], v[160:163], v[212:215], v[34:37]
	v_mfma_f32_16x16x32_bf16 v[34:37], v[164:167], v[216:219], v[34:37]
	v_mfma_f32_16x16x32_bf16 v[26:29], v[168:171], v[212:215], v[26:29]
	v_mfma_f32_16x16x32_bf16 v[26:29], v[172:175], v[216:219], v[26:29]
	v_mfma_f32_16x16x32_bf16 v[22:25], v[176:179], v[212:215], v[22:25]
	v_mfma_f32_16x16x32_bf16 v[22:25], v[184:187], v[216:219], v[22:25]
	v_mfma_f32_16x16x32_bf16 v[14:17], v[188:191], v[212:215], v[14:17]
	v_mfma_f32_16x16x32_bf16 v[14:17], v[192:195], v[216:219], v[14:17]
	v_mfma_f32_16x16x32_bf16 v[18:21], v[160:163], v[220:223], v[18:21]
	v_mfma_f32_16x16x32_bf16 v[18:21], v[164:167], v[224:227], v[18:21]
	v_mfma_f32_16x16x32_bf16 v[10:13], v[168:171], v[220:223], v[10:13]
	v_mfma_f32_16x16x32_bf16 v[10:13], v[172:175], v[224:227], v[10:13]
	v_mfma_f32_16x16x32_bf16 v[6:9], v[176:179], v[220:223], v[6:9]
	v_mfma_f32_16x16x32_bf16 v[6:9], v[184:187], v[224:227], v[6:9]
	v_mfma_f32_16x16x32_bf16 v[2:5], v[188:191], v[220:223], v[2:5]
	v_mfma_f32_16x16x32_bf16 v[2:5], v[192:195], v[224:227], v[2:5]
	s_setprio 0
	s_barrier
	s_add_i32 s90, 0, 0x18000
	v_add_u32_e32 v138, s90, v151
	s_add_i32 s91, 0, 0x1c000
	ds_read_b128 v[160:163], v138
	ds_read_b128 v[164:167], v138 offset:1024
	ds_read_b128 v[168:171], v138 offset:2048
	ds_read_b128 v[172:175], v138 offset:3072
	v_add_u32_e32 v138, s91, v151
	ds_read_b128 v[176:179], v138
	ds_read_b128 v[184:187], v138 offset:1024
	ds_read_b128 v[188:191], v138 offset:2048
	ds_read_b128 v[192:195], v138 offset:3072
	s_add_u32 s50, s50, 0x100000
	s_addc_u32 s51, s51, 0
	s_mov_b32 m0, s66
	ds_read_b128 v[196:199], v157 offset:32768
	ds_read_b128 v[200:203], v157 offset:33792
	ds_read_b128 v[204:207], v157 offset:34816
	ds_read_b128 v[208:211], v157 offset:35840
	ds_read_b128 v[212:215], v157 offset:36864
	ds_read_b128 v[216:219], v157 offset:37888
	ds_read_b128 v[220:223], v157 offset:38912
	ds_read_b128 v[224:227], v157 offset:39936
	global_load_lds_dwordx4 v130, s[50:51]
	s_mov_b32 m0, s67
	s_nop 0
	global_load_lds_dwordx4 v134, s[50:51]
	s_waitcnt vmcnt(8)
	s_waitcnt lgkmcnt(0)
	s_barrier
	s_setprio 1
	s_waitcnt lgkmcnt(0)
	v_mfma_f32_16x16x32_bf16 v[126:129], v[160:163], v[196:199], v[126:129]
	v_mfma_f32_16x16x32_bf16 v[126:129], v[164:167], v[200:203], v[126:129]
	v_mfma_f32_16x16x32_bf16 v[122:125], v[168:171], v[196:199], v[122:125]
	v_mfma_f32_16x16x32_bf16 v[122:125], v[172:175], v[200:203], v[122:125]
	v_mfma_f32_16x16x32_bf16 v[118:121], v[176:179], v[196:199], v[118:121]
	v_mfma_f32_16x16x32_bf16 v[118:121], v[184:187], v[200:203], v[118:121]
	v_mfma_f32_16x16x32_bf16 v[114:117], v[188:191], v[196:199], v[114:117]
	v_mfma_f32_16x16x32_bf16 v[114:117], v[192:195], v[200:203], v[114:117]
	v_mfma_f32_16x16x32_bf16 v[110:113], v[160:163], v[204:207], v[110:113]
	v_mfma_f32_16x16x32_bf16 v[110:113], v[164:167], v[208:211], v[110:113]
	v_mfma_f32_16x16x32_bf16 v[106:109], v[168:171], v[204:207], v[106:109]
	v_mfma_f32_16x16x32_bf16 v[106:109], v[172:175], v[208:211], v[106:109]
	v_mfma_f32_16x16x32_bf16 v[102:105], v[176:179], v[204:207], v[102:105]
	v_mfma_f32_16x16x32_bf16 v[102:105], v[184:187], v[208:211], v[102:105]
	v_mfma_f32_16x16x32_bf16 v[98:101], v[188:191], v[204:207], v[98:101]
	v_mfma_f32_16x16x32_bf16 v[98:101], v[192:195], v[208:211], v[98:101]
	v_mfma_f32_16x16x32_bf16 v[94:97], v[160:163], v[212:215], v[94:97]
	v_mfma_f32_16x16x32_bf16 v[94:97], v[164:167], v[216:219], v[94:97]
	v_mfma_f32_16x16x32_bf16 v[90:93], v[168:171], v[212:215], v[90:93]
	v_mfma_f32_16x16x32_bf16 v[90:93], v[172:175], v[216:219], v[90:93]
	v_mfma_f32_16x16x32_bf16 v[86:89], v[176:179], v[212:215], v[86:89]
	v_mfma_f32_16x16x32_bf16 v[86:89], v[184:187], v[216:219], v[86:89]
	v_mfma_f32_16x16x32_bf16 v[82:85], v[188:191], v[212:215], v[82:85]
	v_mfma_f32_16x16x32_bf16 v[82:85], v[192:195], v[216:219], v[82:85]
	v_mfma_f32_16x16x32_bf16 v[78:81], v[160:163], v[220:223], v[78:81]
	v_mfma_f32_16x16x32_bf16 v[78:81], v[164:167], v[224:227], v[78:81]
	v_mfma_f32_16x16x32_bf16 v[74:77], v[168:171], v[220:223], v[74:77]
	v_mfma_f32_16x16x32_bf16 v[74:77], v[172:175], v[224:227], v[74:77]
	v_mfma_f32_16x16x32_bf16 v[70:73], v[176:179], v[220:223], v[70:73]
	v_mfma_f32_16x16x32_bf16 v[70:73], v[184:187], v[224:227], v[70:73]
	v_mfma_f32_16x16x32_bf16 v[66:69], v[188:191], v[220:223], v[66:69]
	v_mfma_f32_16x16x32_bf16 v[66:69], v[192:195], v[224:227], v[66:69]
	s_setprio 0
	s_barrier
	s_add_i32 s50, s90, s27
	s_mov_b32 m0, s50
	ds_read_b128 v[196:199], v157 offset:49152
	ds_read_b128 v[200:203], v157 offset:50176
	ds_read_b128 v[204:207], v157 offset:51200
	ds_read_b128 v[208:211], v157 offset:52224
	ds_read_b128 v[212:215], v157 offset:53248
	ds_read_b128 v[216:219], v157 offset:54272
	ds_read_b128 v[220:223], v157 offset:55296
	ds_read_b128 v[224:227], v157 offset:56320
	global_load_lds_dwordx4 v132, s[98:99]
	s_add_i32 m0, s50, 0x2000
	s_add_u32 s48, s48, 0x100080
	s_addc_u32 s49, s49, 0
	s_add_i32 s50, s91, s27
	global_load_lds_dwordx4 v136, s[98:99]
	s_mov_b32 m0, s50
	s_nop 0
	global_load_lds_dwordx4 v132, s[48:49]
	s_add_i32 m0, s50, 0x2000
	s_nop 0
	global_load_lds_dwordx4 v136, s[48:49]
	s_mov_b32 m0, s69
	s_nop 0
	global_load_lds_dwordx4 v130, s[100:101]
	s_mov_b32 m0, s70
	s_nop 0
	global_load_lds_dwordx4 v134, s[100:101]
	s_waitcnt vmcnt(8)
	s_waitcnt lgkmcnt(0)
	s_barrier
	s_setprio 1
	s_waitcnt lgkmcnt(0)
	v_mfma_f32_16x16x32_bf16 v[62:65], v[160:163], v[196:199], v[62:65]
	v_mfma_f32_16x16x32_bf16 v[62:65], v[164:167], v[200:203], v[62:65]
	v_mfma_f32_16x16x32_bf16 v[58:61], v[168:171], v[196:199], v[58:61]
	v_mfma_f32_16x16x32_bf16 v[58:61], v[172:175], v[200:203], v[58:61]
	v_mfma_f32_16x16x32_bf16 v[54:57], v[176:179], v[196:199], v[54:57]
	v_mfma_f32_16x16x32_bf16 v[54:57], v[184:187], v[200:203], v[54:57]
	v_mfma_f32_16x16x32_bf16 v[46:49], v[188:191], v[196:199], v[46:49]
	v_mfma_f32_16x16x32_bf16 v[46:49], v[192:195], v[200:203], v[46:49]
	v_mfma_f32_16x16x32_bf16 v[50:53], v[160:163], v[204:207], v[50:53]
	v_mfma_f32_16x16x32_bf16 v[50:53], v[164:167], v[208:211], v[50:53]
	v_mfma_f32_16x16x32_bf16 v[42:45], v[168:171], v[204:207], v[42:45]
	v_mfma_f32_16x16x32_bf16 v[42:45], v[172:175], v[208:211], v[42:45]
	v_mfma_f32_16x16x32_bf16 v[38:41], v[176:179], v[204:207], v[38:41]
	v_mfma_f32_16x16x32_bf16 v[38:41], v[184:187], v[208:211], v[38:41]
	v_mfma_f32_16x16x32_bf16 v[30:33], v[188:191], v[204:207], v[30:33]
	v_mfma_f32_16x16x32_bf16 v[30:33], v[192:195], v[208:211], v[30:33]
	v_mfma_f32_16x16x32_bf16 v[34:37], v[160:163], v[212:215], v[34:37]
	v_mfma_f32_16x16x32_bf16 v[34:37], v[164:167], v[216:219], v[34:37]
	v_mfma_f32_16x16x32_bf16 v[26:29], v[168:171], v[212:215], v[26:29]
	v_mfma_f32_16x16x32_bf16 v[26:29], v[172:175], v[216:219], v[26:29]
	v_mfma_f32_16x16x32_bf16 v[22:25], v[176:179], v[212:215], v[22:25]
	v_mfma_f32_16x16x32_bf16 v[22:25], v[184:187], v[216:219], v[22:25]
	v_mfma_f32_16x16x32_bf16 v[14:17], v[188:191], v[212:215], v[14:17]
	v_mfma_f32_16x16x32_bf16 v[14:17], v[192:195], v[216:219], v[14:17]
	v_mfma_f32_16x16x32_bf16 v[18:21], v[160:163], v[220:223], v[18:21]
	v_mfma_f32_16x16x32_bf16 v[18:21], v[164:167], v[224:227], v[18:21]
	v_mfma_f32_16x16x32_bf16 v[10:13], v[168:171], v[220:223], v[10:13]
	v_mfma_f32_16x16x32_bf16 v[10:13], v[172:175], v[224:227], v[10:13]
	v_mfma_f32_16x16x32_bf16 v[6:9], v[176:179], v[220:223], v[6:9]
	v_mfma_f32_16x16x32_bf16 v[6:9], v[184:187], v[224:227], v[6:9]
	v_mfma_f32_16x16x32_bf16 v[2:5], v[188:191], v[220:223], v[2:5]
	v_mfma_f32_16x16x32_bf16 v[2:5], v[192:195], v[224:227], v[2:5]
	s_setprio 0
	s_barrier
	s_add_i32 s89, s89, 2
	s_add_u32 s6, s6, 0x100
	s_addc_u32 s7, s7, 0
	s_add_u32 s87, s87, 0x100
	s_addc_u32 s88, s88, 0
	s_cmp_gt_u32 s89, 61
	s_cbranch_scc0 .LBB0_2494
	s_and_b64 vcc, exec, s[38:39]
	s_cbranch_vccz .LBB0_2497
	s_barrier

.LBB0_2635:
	ds_read_b128 v[130:133], v163
	ds_read_b128 v[134:137], v163 offset:1024
	ds_read_b128 v[138:141], v163 offset:2048
	ds_read_b128 v[142:145], v163 offset:3072
	ds_read_b128 v[146:149], v188
	ds_read_b128 v[150:153], v188 offset:1024
	ds_read_b128 v[174:177], v188 offset:2048
	ds_read_b128 v[178:181], v188 offset:3072
	s_add_u32 s48, s46, 0xfff00080
	s_addc_u32 s49, s47, -1
	s_cmp_eq_u32 s73, 60
	s_cselect_b32 s51, s22, s49
	s_cselect_b32 s50, s41, s48
	s_cselect_b32 s49, s39, s72
	s_cselect_b32 s48, s70, s71
	s_add_i32 m0, s13, 0xc000
	ds_read_b128 v[184:187], v189
	ds_read_b128 v[192:195], v189 offset:1024
	ds_read_b128 v[196:199], v189 offset:2048
	ds_read_b128 v[200:203], v189 offset:3072
	ds_read_b128 v[204:207], v189 offset:4096
	ds_read_b128 v[208:211], v189 offset:5120
	ds_read_b128 v[212:215], v189 offset:6144
	ds_read_b128 v[216:219], v189 offset:7168
	global_load_lds_dwordx4 v166, s[46:47]
	s_add_i32 m0, s13, 0xe000
	s_nop 0
	global_load_lds_dwordx4 v168, s[46:47]
	s_waitcnt vmcnt(8)
	s_waitcnt lgkmcnt(0)
	s_barrier
	s_setprio 1
	s_waitcnt lgkmcnt(0)
	v_mfma_f32_16x16x32_bf16 v[126:129], v[130:133], v[184:187], v[126:129]
	v_mfma_f32_16x16x32_bf16 v[126:129], v[134:137], v[192:195], v[126:129]
	v_mfma_f32_16x16x32_bf16 v[122:125], v[138:141], v[184:187], v[122:125]
	v_mfma_f32_16x16x32_bf16 v[122:125], v[142:145], v[192:195], v[122:125]
	v_mfma_f32_16x16x32_bf16 v[118:121], v[146:149], v[184:187], v[118:121]
	v_mfma_f32_16x16x32_bf16 v[118:121], v[150:153], v[192:195], v[118:121]
	v_mfma_f32_16x16x32_bf16 v[114:117], v[174:177], v[184:187], v[114:117]
	v_mfma_f32_16x16x32_bf16 v[114:117], v[178:181], v[192:195], v[114:117]
	v_mfma_f32_16x16x32_bf16 v[110:113], v[130:133], v[196:199], v[110:113]
	v_mfma_f32_16x16x32_bf16 v[110:113], v[134:137], v[200:203], v[110:113]
	v_mfma_f32_16x16x32_bf16 v[106:109], v[138:141], v[196:199], v[106:109]
	v_mfma_f32_16x16x32_bf16 v[106:109], v[142:145], v[200:203], v[106:109]
	v_mfma_f32_16x16x32_bf16 v[102:105], v[146:149], v[196:199], v[102:105]
	v_mfma_f32_16x16x32_bf16 v[102:105], v[150:153], v[200:203], v[102:105]
	v_mfma_f32_16x16x32_bf16 v[98:101], v[174:177], v[196:199], v[98:101]
	v_mfma_f32_16x16x32_bf16 v[98:101], v[178:181], v[200:203], v[98:101]
	v_mfma_f32_16x16x32_bf16 v[94:97], v[130:133], v[204:207], v[94:97]
	v_mfma_f32_16x16x32_bf16 v[94:97], v[134:137], v[208:211], v[94:97]
	v_mfma_f32_16x16x32_bf16 v[90:93], v[138:141], v[204:207], v[90:93]
	v_mfma_f32_16x16x32_bf16 v[90:93], v[142:145], v[208:211], v[90:93]
	v_mfma_f32_16x16x32_bf16 v[86:89], v[146:149], v[204:207], v[86:89]
	v_mfma_f32_16x16x32_bf16 v[86:89], v[150:153], v[208:211], v[86:89]
	v_mfma_f32_16x16x32_bf16 v[82:85], v[174:177], v[204:207], v[82:85]
	v_mfma_f32_16x16x32_bf16 v[82:85], v[178:181], v[208:211], v[82:85]
	v_mfma_f32_16x16x32_bf16 v[78:81], v[130:133], v[212:215], v[78:81]
	v_mfma_f32_16x16x32_bf16 v[78:81], v[134:137], v[216:219], v[78:81]
	v_mfma_f32_16x16x32_bf16 v[74:77], v[138:141], v[212:215], v[74:77]
	v_mfma_f32_16x16x32_bf16 v[74:77], v[142:145], v[216:219], v[74:77]
	v_mfma_f32_16x16x32_bf16 v[70:73], v[146:149], v[212:215], v[70:73]
	v_mfma_f32_16x16x32_bf16 v[70:73], v[150:153], v[216:219], v[70:73]
	v_mfma_f32_16x16x32_bf16 v[66:69], v[174:177], v[212:215], v[66:69]
	v_mfma_f32_16x16x32_bf16 v[66:69], v[178:181], v[216:219], v[66:69]
	s_setprio 0
	s_barrier
	s_add_i32 s74, s67, s3
	s_add_u32 s98, s48, 0x80
	s_addc_u32 s99, s49, 0
	s_mov_b32 m0, s74
	ds_read_b128 v[184:187], v189 offset:16384
	ds_read_b128 v[192:195], v189 offset:17408
	ds_read_b128 v[196:199], v189 offset:18432
	ds_read_b128 v[200:203], v189 offset:19456
	ds_read_b128 v[204:207], v189 offset:20480
	ds_read_b128 v[208:211], v189 offset:21504
	ds_read_b128 v[212:215], v189 offset:22528
	ds_read_b128 v[216:219], v189 offset:23552
	global_load_lds_dwordx4 v156, s[48:49]
	s_add_i32 m0, s74, 0x2000
	s_add_u32 s74, s48, 0x100000
	s_addc_u32 s75, s49, 0
	s_add_i32 s76, s68, s3
	global_load_lds_dwordx4 v160, s[48:49]
	s_mov_b32 m0, s76
	global_load_lds_dwordx4 v156, s[74:75]
	s_add_i32 m0, s76, 0x2000
	s_nop 0
	global_load_lds_dwordx4 v160, s[74:75]
	s_add_u32 s100, s50, 0x80
	s_addc_u32 s101, s51, 0
	s_mov_b32 m0, s13
	s_nop 0
	global_load_lds_dwordx4 v154, s[50:51]
	s_mov_b32 m0, s21
	s_nop 0
	global_load_lds_dwordx4 v158, s[50:51]
	s_waitcnt vmcnt(8)
	s_waitcnt lgkmcnt(0)
	s_barrier
	s_setprio 1
	s_waitcnt lgkmcnt(0)
	v_mfma_f32_16x16x32_bf16 v[62:65], v[130:133], v[184:187], v[62:65]
	v_mfma_f32_16x16x32_bf16 v[62:65], v[134:137], v[192:195], v[62:65]
	v_mfma_f32_16x16x32_bf16 v[58:61], v[138:141], v[184:187], v[58:61]
	v_mfma_f32_16x16x32_bf16 v[58:61], v[142:145], v[192:195], v[58:61]
	v_mfma_f32_16x16x32_bf16 v[54:57], v[146:149], v[184:187], v[54:57]
	v_mfma_f32_16x16x32_bf16 v[54:57], v[150:153], v[192:195], v[54:57]
	v_mfma_f32_16x16x32_bf16 v[50:53], v[174:177], v[184:187], v[50:53]
	v_mfma_f32_16x16x32_bf16 v[50:53], v[178:181], v[192:195], v[50:53]
	v_mfma_f32_16x16x32_bf16 v[46:49], v[130:133], v[196:199], v[46:49]
	v_mfma_f32_16x16x32_bf16 v[46:49], v[134:137], v[200:203], v[46:49]
	v_mfma_f32_16x16x32_bf16 v[42:45], v[138:141], v[196:199], v[42:45]
	v_mfma_f32_16x16x32_bf16 v[42:45], v[142:145], v[200:203], v[42:45]
	v_mfma_f32_16x16x32_bf16 v[38:41], v[146:149], v[196:199], v[38:41]
	v_mfma_f32_16x16x32_bf16 v[38:41], v[150:153], v[200:203], v[38:41]
	v_mfma_f32_16x16x32_bf16 v[34:37], v[174:177], v[196:199], v[34:37]
	v_mfma_f32_16x16x32_bf16 v[34:37], v[178:181], v[200:203], v[34:37]
	v_mfma_f32_16x16x32_bf16 v[30:33], v[130:133], v[204:207], v[30:33]
	v_mfma_f32_16x16x32_bf16 v[30:33], v[134:137], v[208:211], v[30:33]
	v_mfma_f32_16x16x32_bf16 v[26:29], v[138:141], v[204:207], v[26:29]
	v_mfma_f32_16x16x32_bf16 v[26:29], v[142:145], v[208:211], v[26:29]
	v_mfma_f32_16x16x32_bf16 v[22:25], v[146:149], v[204:207], v[22:25]
	v_mfma_f32_16x16x32_bf16 v[22:25], v[150:153], v[208:211], v[22:25]
	v_mfma_f32_16x16x32_bf16 v[18:21], v[174:177], v[204:207], v[18:21]
	v_mfma_f32_16x16x32_bf16 v[18:21], v[178:181], v[208:211], v[18:21]
	v_mfma_f32_16x16x32_bf16 v[14:17], v[130:133], v[212:215], v[14:17]
	v_mfma_f32_16x16x32_bf16 v[14:17], v[134:137], v[216:219], v[14:17]
	v_mfma_f32_16x16x32_bf16 v[10:13], v[138:141], v[212:215], v[10:13]
	v_mfma_f32_16x16x32_bf16 v[10:13], v[142:145], v[216:219], v[10:13]
	v_mfma_f32_16x16x32_bf16 v[6:9], v[146:149], v[212:215], v[6:9]
	v_mfma_f32_16x16x32_bf16 v[6:9], v[150:153], v[216:219], v[6:9]
	v_mfma_f32_16x16x32_bf16 v[2:5], v[174:177], v[212:215], v[2:5]
	v_mfma_f32_16x16x32_bf16 v[2:5], v[178:181], v[216:219], v[2:5]
	s_setprio 0
	s_barrier
	s_add_i32 s74, 0, 0x18000
	s_add_i32 s75, 0, 0x1c000
	v_add_u32_e32 v142, s74, v1
	v_add_u32_e32 v178, s75, v1
	ds_read_b128 v[130:133], v142
	ds_read_b128 v[134:137], v142 offset:1024
	ds_read_b128 v[138:141], v142 offset:2048
	ds_read_b128 v[142:145], v142 offset:3072
	ds_read_b128 v[146:149], v178
	ds_read_b128 v[150:153], v178 offset:1024
	ds_read_b128 v[174:177], v178 offset:2048
	ds_read_b128 v[178:181], v178 offset:3072
	s_add_u32 s50, s50, 0x100000
	s_addc_u32 s51, s51, 0
	s_mov_b32 m0, s33
	ds_read_b128 v[184:187], v189 offset:32768
	ds_read_b128 v[192:195], v189 offset:33792
	ds_read_b128 v[196:199], v189 offset:34816
	ds_read_b128 v[200:203], v189 offset:35840
	ds_read_b128 v[204:207], v189 offset:36864
	ds_read_b128 v[208:211], v189 offset:37888
	ds_read_b128 v[212:215], v189 offset:38912
	ds_read_b128 v[216:219], v189 offset:39936
	global_load_lds_dwordx4 v154, s[50:51]
	s_mov_b32 m0, s35
	s_nop 0
	global_load_lds_dwordx4 v158, s[50:51]
	s_waitcnt vmcnt(8)
	s_waitcnt lgkmcnt(0)
	s_barrier
	s_setprio 1
	s_waitcnt lgkmcnt(0)
	v_mfma_f32_16x16x32_bf16 v[126:129], v[130:133], v[184:187], v[126:129]
	v_mfma_f32_16x16x32_bf16 v[126:129], v[134:137], v[192:195], v[126:129]
	v_mfma_f32_16x16x32_bf16 v[122:125], v[138:141], v[184:187], v[122:125]
	v_mfma_f32_16x16x32_bf16 v[122:125], v[142:145], v[192:195], v[122:125]
	v_mfma_f32_16x16x32_bf16 v[118:121], v[146:149], v[184:187], v[118:121]
	v_mfma_f32_16x16x32_bf16 v[118:121], v[150:153], v[192:195], v[118:121]
	v_mfma_f32_16x16x32_bf16 v[114:117], v[174:177], v[184:187], v[114:117]
	v_mfma_f32_16x16x32_bf16 v[114:117], v[178:181], v[192:195], v[114:117]
	v_mfma_f32_16x16x32_bf16 v[110:113], v[130:133], v[196:199], v[110:113]
	v_mfma_f32_16x16x32_bf16 v[110:113], v[134:137], v[200:203], v[110:113]
	v_mfma_f32_16x16x32_bf16 v[106:109], v[138:141], v[196:199], v[106:109]
	v_mfma_f32_16x16x32_bf16 v[106:109], v[142:145], v[200:203], v[106:109]
	v_mfma_f32_16x16x32_bf16 v[102:105], v[146:149], v[196:199], v[102:105]
	v_mfma_f32_16x16x32_bf16 v[102:105], v[150:153], v[200:203], v[102:105]
	v_mfma_f32_16x16x32_bf16 v[98:101], v[174:177], v[196:199], v[98:101]
	v_mfma_f32_16x16x32_bf16 v[98:101], v[178:181], v[200:203], v[98:101]
	v_mfma_f32_16x16x32_bf16 v[94:97], v[130:133], v[204:207], v[94:97]
	v_mfma_f32_16x16x32_bf16 v[94:97], v[134:137], v[208:211], v[94:97]
	v_mfma_f32_16x16x32_bf16 v[90:93], v[138:141], v[204:207], v[90:93]
	v_mfma_f32_16x16x32_bf16 v[90:93], v[142:145], v[208:211], v[90:93]
	v_mfma_f32_16x16x32_bf16 v[86:89], v[146:149], v[204:207], v[86:89]
	v_mfma_f32_16x16x32_bf16 v[86:89], v[150:153], v[208:211], v[86:89]
	v_mfma_f32_16x16x32_bf16 v[82:85], v[174:177], v[204:207], v[82:85]
	v_mfma_f32_16x16x32_bf16 v[82:85], v[178:181], v[208:211], v[82:85]
	v_mfma_f32_16x16x32_bf16 v[78:81], v[130:133], v[212:215], v[78:81]
	v_mfma_f32_16x16x32_bf16 v[78:81], v[134:137], v[216:219], v[78:81]
	v_mfma_f32_16x16x32_bf16 v[74:77], v[138:141], v[212:215], v[74:77]
	v_mfma_f32_16x16x32_bf16 v[74:77], v[142:145], v[216:219], v[74:77]
	v_mfma_f32_16x16x32_bf16 v[70:73], v[146:149], v[212:215], v[70:73]
	v_mfma_f32_16x16x32_bf16 v[70:73], v[150:153], v[216:219], v[70:73]
	v_mfma_f32_16x16x32_bf16 v[66:69], v[174:177], v[212:215], v[66:69]
	v_mfma_f32_16x16x32_bf16 v[66:69], v[178:181], v[216:219], v[66:69]
	s_setprio 0
	s_barrier
	s_add_i32 s50, s74, s3
	s_mov_b32 m0, s50
	ds_read_b128 v[184:187], v189 offset:49152
	ds_read_b128 v[192:195], v189 offset:50176
	ds_read_b128 v[196:199], v189 offset:51200
	ds_read_b128 v[200:203], v189 offset:52224
	ds_read_b128 v[204:207], v189 offset:53248
	ds_read_b128 v[208:211], v189 offset:54272
	ds_read_b128 v[212:215], v189 offset:55296
	ds_read_b128 v[216:219], v189 offset:56320
	global_load_lds_dwordx4 v156, s[98:99]
	s_add_i32 m0, s50, 0x2000
	s_add_u32 s48, s48, 0x100080
	s_addc_u32 s49, s49, 0
	s_add_i32 s50, s75, s3
	global_load_lds_dwordx4 v160, s[98:99]
	s_mov_b32 m0, s50
	s_nop 0
	global_load_lds_dwordx4 v156, s[48:49]
	s_add_i32 m0, s50, 0x2000
	s_nop 0
	global_load_lds_dwordx4 v160, s[48:49]
	s_mov_b32 m0, s62
	s_nop 0
	global_load_lds_dwordx4 v154, s[100:101]
	s_mov_b32 m0, s63
	s_nop 0
	global_load_lds_dwordx4 v158, s[100:101]
	s_waitcnt vmcnt(8)
	s_waitcnt lgkmcnt(0)
	s_barrier
	s_setprio 1
	s_waitcnt lgkmcnt(0)
	v_mfma_f32_16x16x32_bf16 v[62:65], v[130:133], v[184:187], v[62:65]
	v_mfma_f32_16x16x32_bf16 v[62:65], v[134:137], v[192:195], v[62:65]
	v_mfma_f32_16x16x32_bf16 v[58:61], v[138:141], v[184:187], v[58:61]
	v_mfma_f32_16x16x32_bf16 v[58:61], v[142:145], v[192:195], v[58:61]
	v_mfma_f32_16x16x32_bf16 v[54:57], v[146:149], v[184:187], v[54:57]
	v_mfma_f32_16x16x32_bf16 v[54:57], v[150:153], v[192:195], v[54:57]
	v_mfma_f32_16x16x32_bf16 v[50:53], v[174:177], v[184:187], v[50:53]
	v_mfma_f32_16x16x32_bf16 v[50:53], v[178:181], v[192:195], v[50:53]
	v_mfma_f32_16x16x32_bf16 v[46:49], v[130:133], v[196:199], v[46:49]
	v_mfma_f32_16x16x32_bf16 v[46:49], v[134:137], v[200:203], v[46:49]
	v_mfma_f32_16x16x32_bf16 v[42:45], v[138:141], v[196:199], v[42:45]
	v_mfma_f32_16x16x32_bf16 v[42:45], v[142:145], v[200:203], v[42:45]
	v_mfma_f32_16x16x32_bf16 v[38:41], v[146:149], v[196:199], v[38:41]
	v_mfma_f32_16x16x32_bf16 v[38:41], v[150:153], v[200:203], v[38:41]
	v_mfma_f32_16x16x32_bf16 v[34:37], v[174:177], v[196:199], v[34:37]
	v_mfma_f32_16x16x32_bf16 v[34:37], v[178:181], v[200:203], v[34:37]
	v_mfma_f32_16x16x32_bf16 v[30:33], v[130:133], v[204:207], v[30:33]
	v_mfma_f32_16x16x32_bf16 v[30:33], v[134:137], v[208:211], v[30:33]
	v_mfma_f32_16x16x32_bf16 v[26:29], v[138:141], v[204:207], v[26:29]
	v_mfma_f32_16x16x32_bf16 v[26:29], v[142:145], v[208:211], v[26:29]
	v_mfma_f32_16x16x32_bf16 v[22:25], v[146:149], v[204:207], v[22:25]
	v_mfma_f32_16x16x32_bf16 v[22:25], v[150:153], v[208:211], v[22:25]
	v_mfma_f32_16x16x32_bf16 v[18:21], v[174:177], v[204:207], v[18:21]
	v_mfma_f32_16x16x32_bf16 v[18:21], v[178:181], v[208:211], v[18:21]
	v_mfma_f32_16x16x32_bf16 v[14:17], v[130:133], v[212:215], v[14:17]
	v_mfma_f32_16x16x32_bf16 v[14:17], v[134:137], v[216:219], v[14:17]
	v_mfma_f32_16x16x32_bf16 v[10:13], v[138:141], v[212:215], v[10:13]
	v_mfma_f32_16x16x32_bf16 v[10:13], v[142:145], v[216:219], v[10:13]
	v_mfma_f32_16x16x32_bf16 v[6:9], v[146:149], v[212:215], v[6:9]
	v_mfma_f32_16x16x32_bf16 v[6:9], v[150:153], v[216:219], v[6:9]
	v_mfma_f32_16x16x32_bf16 v[2:5], v[174:177], v[212:215], v[2:5]
	v_mfma_f32_16x16x32_bf16 v[2:5], v[178:181], v[216:219], v[2:5]
	s_setprio 0
	s_barrier
	s_add_i32 s73, s73, 2
	s_add_u32 s46, s46, 0x100
	s_addc_u32 s47, s47, 0
	s_add_u32 s71, s71, 0x100
	s_addc_u32 s72, s72, 0
	s_cmp_gt_u32 s73, 61
	s_cbranch_scc0 .LBB0_2635
	s_and_b64 vcc, exec, s[36:37]
	s_cbranch_vccz .LBB0_2638
	s_barrier

.LBB0_2720:
	ds_read_b128 v[148:151], v159
	ds_read_b128 v[164:167], v159 offset:1024
	ds_read_b128 v[168:171], v159 offset:2048
	ds_read_b128 v[172:175], v159 offset:3072
	ds_read_b128 v[176:179], v160
	ds_read_b128 v[184:187], v160 offset:1024
	ds_read_b128 v[188:191], v160 offset:2048
	ds_read_b128 v[192:195], v160 offset:3072
	s_add_u32 s40, s6, 0xfff00080
	s_addc_u32 s41, s7, -1
	s_cmp_eq_u32 s82, 60
	s_cselect_b32 s43, s29, s41
	s_cselect_b32 s42, s78, s40
	s_cselect_b32 s41, s27, s81
	s_cselect_b32 s40, s79, s80
	s_add_i32 m0, s44, 0xc000
	ds_read_b128 v[196:199], v161
	ds_read_b128 v[200:203], v161 offset:1024
	ds_read_b128 v[204:207], v161 offset:2048
	ds_read_b128 v[208:211], v161 offset:3072
	ds_read_b128 v[212:215], v161 offset:4096
	ds_read_b128 v[216:219], v161 offset:5120
	ds_read_b128 v[220:223], v161 offset:6144
	ds_read_b128 v[224:227], v161 offset:7168
	global_load_lds_dwordx4 v140, s[6:7]
	s_add_i32 m0, s44, 0xe000
	s_nop 0
	global_load_lds_dwordx4 v142, s[6:7]
	s_waitcnt vmcnt(8)
	s_waitcnt lgkmcnt(0)
	s_barrier
	s_setprio 1
	s_waitcnt lgkmcnt(0)
	v_mfma_f32_16x16x32_bf16 v[126:129], v[148:151], v[196:199], v[126:129]
	v_mfma_f32_16x16x32_bf16 v[126:129], v[164:167], v[200:203], v[126:129]
	v_mfma_f32_16x16x32_bf16 v[118:121], v[168:171], v[196:199], v[118:121]
	v_mfma_f32_16x16x32_bf16 v[118:121], v[172:175], v[200:203], v[118:121]
	v_mfma_f32_16x16x32_bf16 v[122:125], v[176:179], v[196:199], v[122:125]
	v_mfma_f32_16x16x32_bf16 v[122:125], v[184:187], v[200:203], v[122:125]
	v_mfma_f32_16x16x32_bf16 v[114:117], v[188:191], v[196:199], v[114:117]
	v_mfma_f32_16x16x32_bf16 v[114:117], v[192:195], v[200:203], v[114:117]
	v_mfma_f32_16x16x32_bf16 v[110:113], v[148:151], v[204:207], v[110:113]
	v_mfma_f32_16x16x32_bf16 v[110:113], v[164:167], v[208:211], v[110:113]
	v_mfma_f32_16x16x32_bf16 v[102:105], v[168:171], v[204:207], v[102:105]
	v_mfma_f32_16x16x32_bf16 v[102:105], v[172:175], v[208:211], v[102:105]
	v_mfma_f32_16x16x32_bf16 v[106:109], v[176:179], v[204:207], v[106:109]
	v_mfma_f32_16x16x32_bf16 v[106:109], v[184:187], v[208:211], v[106:109]
	v_mfma_f32_16x16x32_bf16 v[98:101], v[188:191], v[204:207], v[98:101]
	v_mfma_f32_16x16x32_bf16 v[98:101], v[192:195], v[208:211], v[98:101]
	v_mfma_f32_16x16x32_bf16 v[94:97], v[148:151], v[212:215], v[94:97]
	v_mfma_f32_16x16x32_bf16 v[94:97], v[164:167], v[216:219], v[94:97]
	v_mfma_f32_16x16x32_bf16 v[86:89], v[168:171], v[212:215], v[86:89]
	v_mfma_f32_16x16x32_bf16 v[86:89], v[172:175], v[216:219], v[86:89]
	v_mfma_f32_16x16x32_bf16 v[90:93], v[176:179], v[212:215], v[90:93]
	v_mfma_f32_16x16x32_bf16 v[90:93], v[184:187], v[216:219], v[90:93]
	v_mfma_f32_16x16x32_bf16 v[82:85], v[188:191], v[212:215], v[82:85]
	v_mfma_f32_16x16x32_bf16 v[82:85], v[192:195], v[216:219], v[82:85]
	v_mfma_f32_16x16x32_bf16 v[78:81], v[148:151], v[220:223], v[78:81]
	v_mfma_f32_16x16x32_bf16 v[78:81], v[164:167], v[224:227], v[78:81]
	v_mfma_f32_16x16x32_bf16 v[70:73], v[168:171], v[220:223], v[70:73]
	v_mfma_f32_16x16x32_bf16 v[70:73], v[172:175], v[224:227], v[70:73]
	v_mfma_f32_16x16x32_bf16 v[74:77], v[176:179], v[220:223], v[74:77]
	v_mfma_f32_16x16x32_bf16 v[74:77], v[184:187], v[224:227], v[74:77]
	v_mfma_f32_16x16x32_bf16 v[66:69], v[188:191], v[220:223], v[66:69]
	v_mfma_f32_16x16x32_bf16 v[66:69], v[192:195], v[224:227], v[66:69]
	s_setprio 0
	s_barrier
	s_add_i32 s83, s68, s13
	s_add_u32 s98, s40, 0x80
	s_addc_u32 s99, s41, 0
	s_mov_b32 m0, s83
	ds_read_b128 v[196:199], v161 offset:16384
	ds_read_b128 v[200:203], v161 offset:17408
	ds_read_b128 v[204:207], v161 offset:18432
	ds_read_b128 v[208:211], v161 offset:19456
	ds_read_b128 v[212:215], v161 offset:20480
	ds_read_b128 v[216:219], v161 offset:21504
	ds_read_b128 v[220:223], v161 offset:22528
	ds_read_b128 v[224:227], v161 offset:23552
	global_load_lds_dwordx4 v132, s[40:41]
	s_add_i32 m0, s83, 0x2000
	s_add_u32 s84, s40, 0x100000
	s_addc_u32 s85, s41, 0
	s_add_i32 s83, s69, s13
	global_load_lds_dwordx4 v136, s[40:41]
	s_mov_b32 m0, s83
	global_load_lds_dwordx4 v132, s[84:85]
	s_add_i32 m0, s83, 0x2000
	s_nop 0
	global_load_lds_dwordx4 v136, s[84:85]
	s_add_u32 s100, s42, 0x80
	s_addc_u32 s101, s43, 0
	s_mov_b32 m0, s44
	s_nop 0
	global_load_lds_dwordx4 v130, s[42:43]
	s_mov_b32 m0, s45
	s_nop 0
	global_load_lds_dwordx4 v134, s[42:43]
	s_waitcnt vmcnt(8)
	s_waitcnt lgkmcnt(0)
	s_barrier
	s_setprio 1
	s_waitcnt lgkmcnt(0)
	v_mfma_f32_16x16x32_bf16 v[62:65], v[148:151], v[196:199], v[62:65]
	v_mfma_f32_16x16x32_bf16 v[62:65], v[164:167], v[200:203], v[62:65]
	v_mfma_f32_16x16x32_bf16 v[54:57], v[168:171], v[196:199], v[54:57]
	v_mfma_f32_16x16x32_bf16 v[54:57], v[172:175], v[200:203], v[54:57]
	v_mfma_f32_16x16x32_bf16 v[58:61], v[176:179], v[196:199], v[58:61]
	v_mfma_f32_16x16x32_bf16 v[58:61], v[184:187], v[200:203], v[58:61]
	v_mfma_f32_16x16x32_bf16 v[50:53], v[188:191], v[196:199], v[50:53]
	v_mfma_f32_16x16x32_bf16 v[50:53], v[192:195], v[200:203], v[50:53]
	v_mfma_f32_16x16x32_bf16 v[46:49], v[148:151], v[204:207], v[46:49]
	v_mfma_f32_16x16x32_bf16 v[46:49], v[164:167], v[208:211], v[46:49]
	v_mfma_f32_16x16x32_bf16 v[38:41], v[168:171], v[204:207], v[38:41]
	v_mfma_f32_16x16x32_bf16 v[38:41], v[172:175], v[208:211], v[38:41]
	v_mfma_f32_16x16x32_bf16 v[42:45], v[176:179], v[204:207], v[42:45]
	v_mfma_f32_16x16x32_bf16 v[42:45], v[184:187], v[208:211], v[42:45]
	v_mfma_f32_16x16x32_bf16 v[34:37], v[188:191], v[204:207], v[34:37]
	v_mfma_f32_16x16x32_bf16 v[34:37], v[192:195], v[208:211], v[34:37]
	v_mfma_f32_16x16x32_bf16 v[30:33], v[148:151], v[212:215], v[30:33]
	v_mfma_f32_16x16x32_bf16 v[30:33], v[164:167], v[216:219], v[30:33]
	v_mfma_f32_16x16x32_bf16 v[22:25], v[168:171], v[212:215], v[22:25]
	v_mfma_f32_16x16x32_bf16 v[22:25], v[172:175], v[216:219], v[22:25]
	v_mfma_f32_16x16x32_bf16 v[26:29], v[176:179], v[212:215], v[26:29]
	v_mfma_f32_16x16x32_bf16 v[26:29], v[184:187], v[216:219], v[26:29]
	v_mfma_f32_16x16x32_bf16 v[18:21], v[188:191], v[212:215], v[18:21]
	v_mfma_f32_16x16x32_bf16 v[18:21], v[192:195], v[216:219], v[18:21]
	v_mfma_f32_16x16x32_bf16 v[14:17], v[148:151], v[220:223], v[14:17]
	v_mfma_f32_16x16x32_bf16 v[14:17], v[164:167], v[224:227], v[14:17]
	v_mfma_f32_16x16x32_bf16 v[6:9], v[168:171], v[220:223], v[6:9]
	v_mfma_f32_16x16x32_bf16 v[6:9], v[172:175], v[224:227], v[6:9]
	v_mfma_f32_16x16x32_bf16 v[10:13], v[176:179], v[220:223], v[10:13]
	v_mfma_f32_16x16x32_bf16 v[10:13], v[184:187], v[224:227], v[10:13]
	v_mfma_f32_16x16x32_bf16 v[2:5], v[188:191], v[220:223], v[2:5]
	v_mfma_f32_16x16x32_bf16 v[2:5], v[192:195], v[224:227], v[2:5]
	s_setprio 0
	s_barrier
	s_add_i32 s83, 0, 0x18000
	v_add_u32_e32 v138, s83, v155
	s_add_i32 s84, 0, 0x1c000
	ds_read_b128 v[148:151], v138
	ds_read_b128 v[164:167], v138 offset:1024
	ds_read_b128 v[168:171], v138 offset:2048
	ds_read_b128 v[172:175], v138 offset:3072
	v_add_u32_e32 v138, s84, v155
	ds_read_b128 v[176:179], v138
	ds_read_b128 v[184:187], v138 offset:1024
	ds_read_b128 v[188:191], v138 offset:2048
	ds_read_b128 v[192:195], v138 offset:3072
	s_add_u32 s42, s42, 0x100000
	s_addc_u32 s43, s43, 0
	s_mov_b32 m0, s46
	ds_read_b128 v[196:199], v161 offset:32768
	ds_read_b128 v[200:203], v161 offset:33792
	ds_read_b128 v[204:207], v161 offset:34816
	ds_read_b128 v[208:211], v161 offset:35840
	ds_read_b128 v[212:215], v161 offset:36864
	ds_read_b128 v[216:219], v161 offset:37888
	ds_read_b128 v[220:223], v161 offset:38912
	ds_read_b128 v[224:227], v161 offset:39936
	global_load_lds_dwordx4 v130, s[42:43]
	s_mov_b32 m0, s47
	s_nop 0
	global_load_lds_dwordx4 v134, s[42:43]
	s_waitcnt vmcnt(8)
	s_waitcnt lgkmcnt(0)
	s_barrier
	s_setprio 1
	s_waitcnt lgkmcnt(0)
	v_mfma_f32_16x16x32_bf16 v[126:129], v[148:151], v[196:199], v[126:129]
	v_mfma_f32_16x16x32_bf16 v[126:129], v[164:167], v[200:203], v[126:129]
	v_mfma_f32_16x16x32_bf16 v[118:121], v[168:171], v[196:199], v[118:121]
	v_mfma_f32_16x16x32_bf16 v[118:121], v[172:175], v[200:203], v[118:121]
	v_mfma_f32_16x16x32_bf16 v[122:125], v[176:179], v[196:199], v[122:125]
	v_mfma_f32_16x16x32_bf16 v[122:125], v[184:187], v[200:203], v[122:125]
	v_mfma_f32_16x16x32_bf16 v[114:117], v[188:191], v[196:199], v[114:117]
	v_mfma_f32_16x16x32_bf16 v[114:117], v[192:195], v[200:203], v[114:117]
	v_mfma_f32_16x16x32_bf16 v[110:113], v[148:151], v[204:207], v[110:113]
	v_mfma_f32_16x16x32_bf16 v[110:113], v[164:167], v[208:211], v[110:113]
	v_mfma_f32_16x16x32_bf16 v[102:105], v[168:171], v[204:207], v[102:105]
	v_mfma_f32_16x16x32_bf16 v[102:105], v[172:175], v[208:211], v[102:105]
	v_mfma_f32_16x16x32_bf16 v[106:109], v[176:179], v[204:207], v[106:109]
	v_mfma_f32_16x16x32_bf16 v[106:109], v[184:187], v[208:211], v[106:109]
	v_mfma_f32_16x16x32_bf16 v[98:101], v[188:191], v[204:207], v[98:101]
	v_mfma_f32_16x16x32_bf16 v[98:101], v[192:195], v[208:211], v[98:101]
	v_mfma_f32_16x16x32_bf16 v[94:97], v[148:151], v[212:215], v[94:97]
	v_mfma_f32_16x16x32_bf16 v[94:97], v[164:167], v[216:219], v[94:97]
	v_mfma_f32_16x16x32_bf16 v[86:89], v[168:171], v[212:215], v[86:89]
	v_mfma_f32_16x16x32_bf16 v[86:89], v[172:175], v[216:219], v[86:89]
	v_mfma_f32_16x16x32_bf16 v[90:93], v[176:179], v[212:215], v[90:93]
	v_mfma_f32_16x16x32_bf16 v[90:93], v[184:187], v[216:219], v[90:93]
	v_mfma_f32_16x16x32_bf16 v[82:85], v[188:191], v[212:215], v[82:85]
	v_mfma_f32_16x16x32_bf16 v[82:85], v[192:195], v[216:219], v[82:85]
	v_mfma_f32_16x16x32_bf16 v[78:81], v[148:151], v[220:223], v[78:81]
	v_mfma_f32_16x16x32_bf16 v[78:81], v[164:167], v[224:227], v[78:81]
	v_mfma_f32_16x16x32_bf16 v[70:73], v[168:171], v[220:223], v[70:73]
	v_mfma_f32_16x16x32_bf16 v[70:73], v[172:175], v[224:227], v[70:73]
	v_mfma_f32_16x16x32_bf16 v[74:77], v[176:179], v[220:223], v[74:77]
	v_mfma_f32_16x16x32_bf16 v[74:77], v[184:187], v[224:227], v[74:77]
	v_mfma_f32_16x16x32_bf16 v[66:69], v[188:191], v[220:223], v[66:69]
	v_mfma_f32_16x16x32_bf16 v[66:69], v[192:195], v[224:227], v[66:69]
	s_setprio 0
	s_barrier
	s_add_i32 s42, s83, s13
	s_mov_b32 m0, s42
	ds_read_b128 v[196:199], v161 offset:49152
	ds_read_b128 v[200:203], v161 offset:50176
	ds_read_b128 v[204:207], v161 offset:51200
	ds_read_b128 v[208:211], v161 offset:52224
	ds_read_b128 v[212:215], v161 offset:53248
	ds_read_b128 v[216:219], v161 offset:54272
	ds_read_b128 v[220:223], v161 offset:55296
	ds_read_b128 v[224:227], v161 offset:56320
	global_load_lds_dwordx4 v132, s[98:99]
	s_add_i32 m0, s42, 0x2000
	s_add_u32 s40, s40, 0x100080
	s_addc_u32 s41, s41, 0
	s_add_i32 s42, s84, s13
	global_load_lds_dwordx4 v136, s[98:99]
	s_mov_b32 m0, s42
	s_nop 0
	global_load_lds_dwordx4 v132, s[40:41]
	s_add_i32 m0, s42, 0x2000
	s_nop 0
	global_load_lds_dwordx4 v136, s[40:41]
	s_mov_b32 m0, s59
	s_nop 0
	global_load_lds_dwordx4 v130, s[100:101]
	s_mov_b32 m0, s62
	s_nop 0
	global_load_lds_dwordx4 v134, s[100:101]
	s_waitcnt vmcnt(8)
	s_waitcnt lgkmcnt(0)
	s_barrier
	s_setprio 1
	s_waitcnt lgkmcnt(0)
	v_mfma_f32_16x16x32_bf16 v[62:65], v[148:151], v[196:199], v[62:65]
	v_mfma_f32_16x16x32_bf16 v[62:65], v[164:167], v[200:203], v[62:65]
	v_mfma_f32_16x16x32_bf16 v[54:57], v[168:171], v[196:199], v[54:57]
	v_mfma_f32_16x16x32_bf16 v[54:57], v[172:175], v[200:203], v[54:57]
	v_mfma_f32_16x16x32_bf16 v[58:61], v[176:179], v[196:199], v[58:61]
	v_mfma_f32_16x16x32_bf16 v[58:61], v[184:187], v[200:203], v[58:61]
	v_mfma_f32_16x16x32_bf16 v[50:53], v[188:191], v[196:199], v[50:53]
	v_mfma_f32_16x16x32_bf16 v[50:53], v[192:195], v[200:203], v[50:53]
	v_mfma_f32_16x16x32_bf16 v[46:49], v[148:151], v[204:207], v[46:49]
	v_mfma_f32_16x16x32_bf16 v[46:49], v[164:167], v[208:211], v[46:49]
	v_mfma_f32_16x16x32_bf16 v[38:41], v[168:171], v[204:207], v[38:41]
	v_mfma_f32_16x16x32_bf16 v[38:41], v[172:175], v[208:211], v[38:41]
	v_mfma_f32_16x16x32_bf16 v[42:45], v[176:179], v[204:207], v[42:45]
	v_mfma_f32_16x16x32_bf16 v[42:45], v[184:187], v[208:211], v[42:45]
	v_mfma_f32_16x16x32_bf16 v[34:37], v[188:191], v[204:207], v[34:37]
	v_mfma_f32_16x16x32_bf16 v[34:37], v[192:195], v[208:211], v[34:37]
	v_mfma_f32_16x16x32_bf16 v[30:33], v[148:151], v[212:215], v[30:33]
	v_mfma_f32_16x16x32_bf16 v[30:33], v[164:167], v[216:219], v[30:33]
	v_mfma_f32_16x16x32_bf16 v[22:25], v[168:171], v[212:215], v[22:25]
	v_mfma_f32_16x16x32_bf16 v[22:25], v[172:175], v[216:219], v[22:25]
	v_mfma_f32_16x16x32_bf16 v[26:29], v[176:179], v[212:215], v[26:29]
	v_mfma_f32_16x16x32_bf16 v[26:29], v[184:187], v[216:219], v[26:29]
	v_mfma_f32_16x16x32_bf16 v[18:21], v[188:191], v[212:215], v[18:21]
	v_mfma_f32_16x16x32_bf16 v[18:21], v[192:195], v[216:219], v[18:21]
	v_mfma_f32_16x16x32_bf16 v[14:17], v[148:151], v[220:223], v[14:17]
	v_mfma_f32_16x16x32_bf16 v[14:17], v[164:167], v[224:227], v[14:17]
	v_mfma_f32_16x16x32_bf16 v[6:9], v[168:171], v[220:223], v[6:9]
	v_mfma_f32_16x16x32_bf16 v[6:9], v[172:175], v[224:227], v[6:9]
	v_mfma_f32_16x16x32_bf16 v[10:13], v[176:179], v[220:223], v[10:13]
	v_mfma_f32_16x16x32_bf16 v[10:13], v[184:187], v[224:227], v[10:13]
	v_mfma_f32_16x16x32_bf16 v[2:5], v[188:191], v[220:223], v[2:5]
	v_mfma_f32_16x16x32_bf16 v[2:5], v[192:195], v[224:227], v[2:5]
	s_setprio 0
	s_barrier
	s_add_i32 s82, s82, 2
	s_add_u32 s6, s6, 0x100
	s_addc_u32 s7, s7, 0
	s_add_u32 s80, s80, 0x100
	s_addc_u32 s81, s81, 0
	s_cmp_gt_u32 s82, 61
	s_cbranch_scc0 .LBB0_2720
	s_and_b64 vcc, exec, s[24:25]
	s_cbranch_vccz .LBB0_2723
	s_barrier

.LBB0_2805:
	ds_read_b128 v[130:133], v163
	ds_read_b128 v[134:137], v163 offset:1024
	ds_read_b128 v[138:141], v163 offset:2048
	ds_read_b128 v[142:145], v163 offset:3072
	ds_read_b128 v[146:149], v188
	ds_read_b128 v[150:153], v188 offset:1024
	ds_read_b128 v[174:177], v188 offset:2048
	ds_read_b128 v[178:181], v188 offset:3072
	s_add_u32 s28, s26, 0xffd50080
	s_addc_u32 s29, s27, -1
	s_cmpk_eq_i32 s62, 0xa8
	s_cselect_b32 s37, s7, s29
	s_cselect_b32 s36, s6, s28
	s_cselect_b32 s29, s25, s59
	s_cselect_b32 s28, s24, s12
	s_add_i32 m0, s38, 0xc000
	ds_read_b128 v[184:187], v189
	ds_read_b128 v[192:195], v189 offset:1024
	ds_read_b128 v[196:199], v189 offset:2048
	ds_read_b128 v[200:203], v189 offset:3072
	ds_read_b128 v[204:207], v189 offset:4096
	ds_read_b128 v[208:211], v189 offset:5120
	ds_read_b128 v[212:215], v189 offset:6144
	ds_read_b128 v[216:219], v189 offset:7168
	global_load_lds_dwordx4 v166, s[26:27]
	s_add_i32 m0, s38, 0xe000
	s_nop 0
	global_load_lds_dwordx4 v168, s[26:27]
	s_waitcnt vmcnt(8)
	s_waitcnt lgkmcnt(0)
	s_barrier
	s_setprio 1
	s_waitcnt lgkmcnt(0)
	v_mfma_f32_16x16x32_bf16 v[126:129], v[130:133], v[184:187], v[126:129]
	v_mfma_f32_16x16x32_bf16 v[126:129], v[134:137], v[192:195], v[126:129]
	v_mfma_f32_16x16x32_bf16 v[122:125], v[138:141], v[184:187], v[122:125]
	v_mfma_f32_16x16x32_bf16 v[122:125], v[142:145], v[192:195], v[122:125]
	v_mfma_f32_16x16x32_bf16 v[118:121], v[146:149], v[184:187], v[118:121]
	v_mfma_f32_16x16x32_bf16 v[118:121], v[150:153], v[192:195], v[118:121]
	v_mfma_f32_16x16x32_bf16 v[114:117], v[174:177], v[184:187], v[114:117]
	v_mfma_f32_16x16x32_bf16 v[114:117], v[178:181], v[192:195], v[114:117]
	v_mfma_f32_16x16x32_bf16 v[110:113], v[130:133], v[196:199], v[110:113]
	v_mfma_f32_16x16x32_bf16 v[110:113], v[134:137], v[200:203], v[110:113]
	v_mfma_f32_16x16x32_bf16 v[106:109], v[138:141], v[196:199], v[106:109]
	v_mfma_f32_16x16x32_bf16 v[106:109], v[142:145], v[200:203], v[106:109]
	v_mfma_f32_16x16x32_bf16 v[102:105], v[146:149], v[196:199], v[102:105]
	v_mfma_f32_16x16x32_bf16 v[102:105], v[150:153], v[200:203], v[102:105]
	v_mfma_f32_16x16x32_bf16 v[98:101], v[174:177], v[196:199], v[98:101]
	v_mfma_f32_16x16x32_bf16 v[98:101], v[178:181], v[200:203], v[98:101]
	v_mfma_f32_16x16x32_bf16 v[94:97], v[130:133], v[204:207], v[94:97]
	v_mfma_f32_16x16x32_bf16 v[94:97], v[134:137], v[208:211], v[94:97]
	v_mfma_f32_16x16x32_bf16 v[90:93], v[138:141], v[204:207], v[90:93]
	v_mfma_f32_16x16x32_bf16 v[90:93], v[142:145], v[208:211], v[90:93]
	v_mfma_f32_16x16x32_bf16 v[86:89], v[146:149], v[204:207], v[86:89]
	v_mfma_f32_16x16x32_bf16 v[86:89], v[150:153], v[208:211], v[86:89]
	v_mfma_f32_16x16x32_bf16 v[82:85], v[174:177], v[204:207], v[82:85]
	v_mfma_f32_16x16x32_bf16 v[82:85], v[178:181], v[208:211], v[82:85]
	v_mfma_f32_16x16x32_bf16 v[78:81], v[130:133], v[212:215], v[78:81]
	v_mfma_f32_16x16x32_bf16 v[78:81], v[134:137], v[216:219], v[78:81]
	v_mfma_f32_16x16x32_bf16 v[74:77], v[138:141], v[212:215], v[74:77]
	v_mfma_f32_16x16x32_bf16 v[74:77], v[142:145], v[216:219], v[74:77]
	v_mfma_f32_16x16x32_bf16 v[70:73], v[146:149], v[212:215], v[70:73]
	v_mfma_f32_16x16x32_bf16 v[70:73], v[150:153], v[216:219], v[70:73]
	v_mfma_f32_16x16x32_bf16 v[66:69], v[174:177], v[212:215], v[66:69]
	v_mfma_f32_16x16x32_bf16 v[66:69], v[178:181], v[216:219], v[66:69]
	s_setprio 0
	s_barrier
	s_add_i32 s63, s47, s35
	s_add_u32 s98, s28, 0x80
	s_addc_u32 s99, s29, 0
	s_mov_b32 m0, s63
	ds_read_b128 v[184:187], v189 offset:16384
	ds_read_b128 v[192:195], v189 offset:17408
	ds_read_b128 v[196:199], v189 offset:18432
	ds_read_b128 v[200:203], v189 offset:19456
	ds_read_b128 v[204:207], v189 offset:20480
	ds_read_b128 v[208:211], v189 offset:21504
	ds_read_b128 v[212:215], v189 offset:22528
	ds_read_b128 v[216:219], v189 offset:23552
	global_load_lds_dwordx4 v156, s[28:29]
	s_add_i32 m0, s63, 0x2000
	s_add_u32 s66, s28, 0x2b0000
	s_addc_u32 s67, s29, 0
	s_add_i32 s63, s48, s35
	global_load_lds_dwordx4 v160, s[28:29]
	s_mov_b32 m0, s63
	global_load_lds_dwordx4 v156, s[66:67]
	s_add_i32 m0, s63, 0x2000
	s_nop 0
	global_load_lds_dwordx4 v160, s[66:67]
	s_add_u32 s100, s36, 0x80
	s_addc_u32 s101, s37, 0
	s_mov_b32 m0, s38
	s_nop 0
	global_load_lds_dwordx4 v154, s[36:37]
	s_mov_b32 m0, s39
	s_nop 0
	global_load_lds_dwordx4 v158, s[36:37]
	s_waitcnt vmcnt(8)
	s_waitcnt lgkmcnt(0)
	s_barrier
	s_setprio 1
	s_waitcnt lgkmcnt(0)
	v_mfma_f32_16x16x32_bf16 v[62:65], v[130:133], v[184:187], v[62:65]
	v_mfma_f32_16x16x32_bf16 v[62:65], v[134:137], v[192:195], v[62:65]
	v_mfma_f32_16x16x32_bf16 v[58:61], v[138:141], v[184:187], v[58:61]
	v_mfma_f32_16x16x32_bf16 v[58:61], v[142:145], v[192:195], v[58:61]
	v_mfma_f32_16x16x32_bf16 v[54:57], v[146:149], v[184:187], v[54:57]
	v_mfma_f32_16x16x32_bf16 v[54:57], v[150:153], v[192:195], v[54:57]
	v_mfma_f32_16x16x32_bf16 v[50:53], v[174:177], v[184:187], v[50:53]
	v_mfma_f32_16x16x32_bf16 v[50:53], v[178:181], v[192:195], v[50:53]
	v_mfma_f32_16x16x32_bf16 v[46:49], v[130:133], v[196:199], v[46:49]
	v_mfma_f32_16x16x32_bf16 v[46:49], v[134:137], v[200:203], v[46:49]
	v_mfma_f32_16x16x32_bf16 v[42:45], v[138:141], v[196:199], v[42:45]
	v_mfma_f32_16x16x32_bf16 v[42:45], v[142:145], v[200:203], v[42:45]
	v_mfma_f32_16x16x32_bf16 v[38:41], v[146:149], v[196:199], v[38:41]
	v_mfma_f32_16x16x32_bf16 v[38:41], v[150:153], v[200:203], v[38:41]
	v_mfma_f32_16x16x32_bf16 v[34:37], v[174:177], v[196:199], v[34:37]
	v_mfma_f32_16x16x32_bf16 v[34:37], v[178:181], v[200:203], v[34:37]
	v_mfma_f32_16x16x32_bf16 v[30:33], v[130:133], v[204:207], v[30:33]
	v_mfma_f32_16x16x32_bf16 v[30:33], v[134:137], v[208:211], v[30:33]
	v_mfma_f32_16x16x32_bf16 v[26:29], v[138:141], v[204:207], v[26:29]
	v_mfma_f32_16x16x32_bf16 v[26:29], v[142:145], v[208:211], v[26:29]
	v_mfma_f32_16x16x32_bf16 v[22:25], v[146:149], v[204:207], v[22:25]
	v_mfma_f32_16x16x32_bf16 v[22:25], v[150:153], v[208:211], v[22:25]
	v_mfma_f32_16x16x32_bf16 v[18:21], v[174:177], v[204:207], v[18:21]
	v_mfma_f32_16x16x32_bf16 v[18:21], v[178:181], v[208:211], v[18:21]
	v_mfma_f32_16x16x32_bf16 v[14:17], v[130:133], v[212:215], v[14:17]
	v_mfma_f32_16x16x32_bf16 v[14:17], v[134:137], v[216:219], v[14:17]
	v_mfma_f32_16x16x32_bf16 v[10:13], v[138:141], v[212:215], v[10:13]
	v_mfma_f32_16x16x32_bf16 v[10:13], v[142:145], v[216:219], v[10:13]
	v_mfma_f32_16x16x32_bf16 v[6:9], v[146:149], v[212:215], v[6:9]
	v_mfma_f32_16x16x32_bf16 v[6:9], v[150:153], v[216:219], v[6:9]
	v_mfma_f32_16x16x32_bf16 v[2:5], v[174:177], v[212:215], v[2:5]
	v_mfma_f32_16x16x32_bf16 v[2:5], v[178:181], v[216:219], v[2:5]
	s_setprio 0
	s_barrier
	s_add_i32 s63, 0, 0x18000
	s_add_i32 s65, 0, 0x1c000
	v_add_u32_e32 v142, s63, v1
	v_add_u32_e32 v178, s65, v1
	ds_read_b128 v[130:133], v142
	ds_read_b128 v[134:137], v142 offset:1024
	ds_read_b128 v[138:141], v142 offset:2048
	ds_read_b128 v[142:145], v142 offset:3072
	ds_read_b128 v[146:149], v178
	ds_read_b128 v[150:153], v178 offset:1024
	ds_read_b128 v[174:177], v178 offset:2048
	ds_read_b128 v[178:181], v178 offset:3072
	s_add_u32 s36, s36, 0x2b0000
	s_addc_u32 s37, s37, 0
	s_mov_b32 m0, s40
	ds_read_b128 v[184:187], v189 offset:32768
	ds_read_b128 v[192:195], v189 offset:33792
	ds_read_b128 v[196:199], v189 offset:34816
	ds_read_b128 v[200:203], v189 offset:35840
	ds_read_b128 v[204:207], v189 offset:36864
	ds_read_b128 v[208:211], v189 offset:37888
	ds_read_b128 v[212:215], v189 offset:38912
	ds_read_b128 v[216:219], v189 offset:39936
	global_load_lds_dwordx4 v154, s[36:37]
	s_mov_b32 m0, s41
	s_nop 0
	global_load_lds_dwordx4 v158, s[36:37]
	s_waitcnt vmcnt(8)
	s_waitcnt lgkmcnt(0)
	s_barrier
	s_setprio 1
	s_waitcnt lgkmcnt(0)
	v_mfma_f32_16x16x32_bf16 v[126:129], v[130:133], v[184:187], v[126:129]
	v_mfma_f32_16x16x32_bf16 v[126:129], v[134:137], v[192:195], v[126:129]
	v_mfma_f32_16x16x32_bf16 v[122:125], v[138:141], v[184:187], v[122:125]
	v_mfma_f32_16x16x32_bf16 v[122:125], v[142:145], v[192:195], v[122:125]
	v_mfma_f32_16x16x32_bf16 v[118:121], v[146:149], v[184:187], v[118:121]
	v_mfma_f32_16x16x32_bf16 v[118:121], v[150:153], v[192:195], v[118:121]
	v_mfma_f32_16x16x32_bf16 v[114:117], v[174:177], v[184:187], v[114:117]
	v_mfma_f32_16x16x32_bf16 v[114:117], v[178:181], v[192:195], v[114:117]
	v_mfma_f32_16x16x32_bf16 v[110:113], v[130:133], v[196:199], v[110:113]
	v_mfma_f32_16x16x32_bf16 v[110:113], v[134:137], v[200:203], v[110:113]
	v_mfma_f32_16x16x32_bf16 v[106:109], v[138:141], v[196:199], v[106:109]
	v_mfma_f32_16x16x32_bf16 v[106:109], v[142:145], v[200:203], v[106:109]
	v_mfma_f32_16x16x32_bf16 v[102:105], v[146:149], v[196:199], v[102:105]
	v_mfma_f32_16x16x32_bf16 v[102:105], v[150:153], v[200:203], v[102:105]
	v_mfma_f32_16x16x32_bf16 v[98:101], v[174:177], v[196:199], v[98:101]
	v_mfma_f32_16x16x32_bf16 v[98:101], v[178:181], v[200:203], v[98:101]
	v_mfma_f32_16x16x32_bf16 v[94:97], v[130:133], v[204:207], v[94:97]
	v_mfma_f32_16x16x32_bf16 v[94:97], v[134:137], v[208:211], v[94:97]
	v_mfma_f32_16x16x32_bf16 v[90:93], v[138:141], v[204:207], v[90:93]
	v_mfma_f32_16x16x32_bf16 v[90:93], v[142:145], v[208:211], v[90:93]
	v_mfma_f32_16x16x32_bf16 v[86:89], v[146:149], v[204:207], v[86:89]
	v_mfma_f32_16x16x32_bf16 v[86:89], v[150:153], v[208:211], v[86:89]
	v_mfma_f32_16x16x32_bf16 v[82:85], v[174:177], v[204:207], v[82:85]
	v_mfma_f32_16x16x32_bf16 v[82:85], v[178:181], v[208:211], v[82:85]
	v_mfma_f32_16x16x32_bf16 v[78:81], v[130:133], v[212:215], v[78:81]
	v_mfma_f32_16x16x32_bf16 v[78:81], v[134:137], v[216:219], v[78:81]
	v_mfma_f32_16x16x32_bf16 v[74:77], v[138:141], v[212:215], v[74:77]
	v_mfma_f32_16x16x32_bf16 v[74:77], v[142:145], v[216:219], v[74:77]
	v_mfma_f32_16x16x32_bf16 v[70:73], v[146:149], v[212:215], v[70:73]
	v_mfma_f32_16x16x32_bf16 v[70:73], v[150:153], v[216:219], v[70:73]
	v_mfma_f32_16x16x32_bf16 v[66:69], v[174:177], v[212:215], v[66:69]
	v_mfma_f32_16x16x32_bf16 v[66:69], v[178:181], v[216:219], v[66:69]
	s_setprio 0
	s_barrier
	s_add_i32 s36, s63, s35
	s_mov_b32 m0, s36
	ds_read_b128 v[184:187], v189 offset:49152
	ds_read_b128 v[192:195], v189 offset:50176
	ds_read_b128 v[196:199], v189 offset:51200
	ds_read_b128 v[200:203], v189 offset:52224
	ds_read_b128 v[204:207], v189 offset:53248
	ds_read_b128 v[208:211], v189 offset:54272
	ds_read_b128 v[212:215], v189 offset:55296
	ds_read_b128 v[216:219], v189 offset:56320
	global_load_lds_dwordx4 v156, s[98:99]
	s_add_i32 m0, s36, 0x2000
	s_add_u32 s28, s28, 0x2b0080
	s_addc_u32 s29, s29, 0
	s_add_i32 s36, s65, s35
	global_load_lds_dwordx4 v160, s[98:99]
	s_mov_b32 m0, s36
	s_nop 0
	global_load_lds_dwordx4 v156, s[28:29]
	s_add_i32 m0, s36, 0x2000
	s_nop 0
	global_load_lds_dwordx4 v160, s[28:29]
	s_mov_b32 m0, s43
	s_nop 0
	global_load_lds_dwordx4 v154, s[100:101]
	s_mov_b32 m0, s44
	s_nop 0
	global_load_lds_dwordx4 v158, s[100:101]
	s_waitcnt vmcnt(8)
	s_waitcnt lgkmcnt(0)
	s_barrier
	s_setprio 1
	s_waitcnt lgkmcnt(0)
	v_mfma_f32_16x16x32_bf16 v[62:65], v[130:133], v[184:187], v[62:65]
	v_mfma_f32_16x16x32_bf16 v[62:65], v[134:137], v[192:195], v[62:65]
	v_mfma_f32_16x16x32_bf16 v[58:61], v[138:141], v[184:187], v[58:61]
	v_mfma_f32_16x16x32_bf16 v[58:61], v[142:145], v[192:195], v[58:61]
	v_mfma_f32_16x16x32_bf16 v[54:57], v[146:149], v[184:187], v[54:57]
	v_mfma_f32_16x16x32_bf16 v[54:57], v[150:153], v[192:195], v[54:57]
	v_mfma_f32_16x16x32_bf16 v[50:53], v[174:177], v[184:187], v[50:53]
	v_mfma_f32_16x16x32_bf16 v[50:53], v[178:181], v[192:195], v[50:53]
	v_mfma_f32_16x16x32_bf16 v[46:49], v[130:133], v[196:199], v[46:49]
	v_mfma_f32_16x16x32_bf16 v[46:49], v[134:137], v[200:203], v[46:49]
	v_mfma_f32_16x16x32_bf16 v[42:45], v[138:141], v[196:199], v[42:45]
	v_mfma_f32_16x16x32_bf16 v[42:45], v[142:145], v[200:203], v[42:45]
	v_mfma_f32_16x16x32_bf16 v[38:41], v[146:149], v[196:199], v[38:41]
	v_mfma_f32_16x16x32_bf16 v[38:41], v[150:153], v[200:203], v[38:41]
	v_mfma_f32_16x16x32_bf16 v[34:37], v[174:177], v[196:199], v[34:37]
	v_mfma_f32_16x16x32_bf16 v[34:37], v[178:181], v[200:203], v[34:37]
	v_mfma_f32_16x16x32_bf16 v[30:33], v[130:133], v[204:207], v[30:33]
	v_mfma_f32_16x16x32_bf16 v[30:33], v[134:137], v[208:211], v[30:33]
	v_mfma_f32_16x16x32_bf16 v[26:29], v[138:141], v[204:207], v[26:29]
	v_mfma_f32_16x16x32_bf16 v[26:29], v[142:145], v[208:211], v[26:29]
	v_mfma_f32_16x16x32_bf16 v[22:25], v[146:149], v[204:207], v[22:25]
	v_mfma_f32_16x16x32_bf16 v[22:25], v[150:153], v[208:211], v[22:25]
	v_mfma_f32_16x16x32_bf16 v[18:21], v[174:177], v[204:207], v[18:21]
	v_mfma_f32_16x16x32_bf16 v[18:21], v[178:181], v[208:211], v[18:21]
	v_mfma_f32_16x16x32_bf16 v[14:17], v[130:133], v[212:215], v[14:17]
	v_mfma_f32_16x16x32_bf16 v[14:17], v[134:137], v[216:219], v[14:17]
	v_mfma_f32_16x16x32_bf16 v[10:13], v[138:141], v[212:215], v[10:13]
	v_mfma_f32_16x16x32_bf16 v[10:13], v[142:145], v[216:219], v[10:13]
	v_mfma_f32_16x16x32_bf16 v[6:9], v[146:149], v[212:215], v[6:9]
	v_mfma_f32_16x16x32_bf16 v[6:9], v[150:153], v[216:219], v[6:9]
	v_mfma_f32_16x16x32_bf16 v[2:5], v[174:177], v[212:215], v[2:5]
	v_mfma_f32_16x16x32_bf16 v[2:5], v[178:181], v[216:219], v[2:5]
	s_setprio 0
	s_barrier
	s_add_i32 s62, s62, 2
	s_add_u32 s26, s26, 0x100
	s_addc_u32 s27, s27, 0
	s_add_u32 s12, s12, 0x100
	s_addc_u32 s59, s59, 0
	s_cmpk_gt_u32 s62, 0xa9
	s_cbranch_scc0 .LBB0_2805
	s_and_b64 vcc, exec, s[22:23]
	s_cbranch_vccz .LBB0_2808
	s_barrier
